# v31
# speedup vs baseline: 1.0084x; 1.0001x over previous
.LBB0_185:
	s_or_b64 exec, exec, s[0:1]
	v_readlane_b32 s0, v247, 45
	v_readlane_b32 s1, v247, 46
	s_andn2_b64 vcc, exec, s[0:1]
	s_barrier
	s_cbranch_vccnz .LBB0_347
	v_mov_b32_e32 v2, v187
	v_readlane_b32 s6, v247, 48
	v_readfirstlane_b32 s0, v2
	s_ashr_i32 s0, s0, 1
	v_readlane_b32 s7, v247, 49
	v_mov_b32_e32 v0, s0
	s_movk_i32 s0, 0xffe0
	v_bfi_b32 v0, s0, v0, v2
	v_ashrrev_i32_e32 v1, 31, v0
	v_lshlrev_b64 v[0:1], 8, v[0:1]
	v_lshrrev_b32_e32 v3, 1, v2
	v_lshl_add_u64 v[0:1], s[6:7], 0, v[0:1]
	v_and_b32_e32 v184, 16, v3
	v_lshl_add_u64 v[0:1], v[0:1], 0, v[184:185]
	global_load_dwordx4 v[124:127], v[0:1], off
	global_load_dwordx4 v[120:123], v[0:1], off offset:32
	global_load_dwordx4 v[116:119], v[0:1], off offset:64
	global_load_dwordx4 v[112:115], v[0:1], off offset:96
	global_load_dwordx4 v[108:111], v[0:1], off offset:128
	global_load_dwordx4 v[104:107], v[0:1], off offset:160
	global_load_dwordx4 v[100:103], v[0:1], off offset:192
	global_load_dwordx4 v[96:99], v[0:1], off offset:224
	v_ashrrev_i32_e32 v0, 4, v2
	v_lshlrev_b32_e32 v1, 4, v2
	v_and_b32_e32 v2, 0x70, v2
	s_movk_i32 s0, 0xf0
	v_and_b32_e32 v184, 0xf0, v1
	v_bitop3_b32 v9, v1, v2, s0 bitop3:0x6c
	v_ashrrev_i32_e32 v1, 31, v0
	v_readlane_b32 s4, v247, 56
	v_lshlrev_b32_e32 v8, 8, v0
	v_lshlrev_b64 v[0:1], 8, v[0:1]
	v_readlane_b32 s5, v247, 57
	s_mov_b64 s[0:1], 0x2000
	v_readlane_b32 s2, v247, 52
	v_lshl_add_u64 v[2:3], s[4:5], 0, v[0:1]
	v_lshl_add_u64 v[2:3], v[2:3], 0, v[184:185]
	v_lshl_add_u64 v[4:5], v[0:1], 0, s[0:1]
	v_readlane_b32 s3, v247, 53
	global_load_dwordx4 v[128:131], v[2:3], off
	v_lshl_add_u64 v[2:3], s[4:5], 0, v[4:5]
	v_lshl_add_u64 v[0:1], s[2:3], 0, v[0:1]
	v_lshl_add_u64 v[2:3], v[2:3], 0, v[184:185]
	v_lshl_add_u64 v[0:1], v[0:1], 0, v[184:185]
	v_lshl_add_u64 v[4:5], s[2:3], 0, v[4:5]
	global_load_dwordx4 v[132:135], v[2:3], off
	v_lshl_add_u64 v[4:5], v[4:5], 0, v[184:185]
	global_load_dwordx4 v[0:3], v[0:1], off
	v_readlane_b32 s16, v247, 58
	global_load_dwordx4 v[4:7], v[4:5], off
	s_waitcnt vmcnt(0)
	v_readlane_b32 s23, v247, 47
	v_readlane_b32 s17, v247, 59
	s_mov_b64 s[0:1], s[4:5]
	v_readlane_b32 s4, v246, 1
	v_lshlrev_b32_e32 v8, 4, v187
	v_and_b32_e32 v9, 0x70, v8
	v_and_b32_e32 v8, 0x80, v8
	v_lshlrev_b32_e32 v8, 6, v8
	v_or_b32_e32 v8, v8, v9
	v_lshrrev_b32_e32 v9, 1, v187
	v_and_b32_e32 v9, 0x70, v9
	v_xor_b32_e32 v8, v8, v9
	v_lshrrev_b32_e32 v9, 4, v187
	v_lshl_add_u32 v8, v9, 7, v8
	s_mov_b32 s20, 0
	s_mov_b32 s21, s4
	s_mov_b32 s22, s23
	s_mov_b64 s[10:11], s[16:17]
	s_mov_b64 s[8:9], s[0:1]
	s_mov_b64 s[12:13], s[2:3]
	v_readlane_b32 s5, v246, 2
	s_waitcnt vmcnt(1)
	ds_write_b128 v8, v[0:3] offset:32768
	s_waitcnt vmcnt(0)
	ds_write_b128 v8, v[4:7] offset:36864
	s_waitcnt lgkmcnt(0)
	s_barrier
	s_branch .LBB0_188

.LBB0_190:
	v_mov_b32_e32 v171, v187
	s_nop 0
	v_readfirstlane_b32 s4, v171
	v_ashrrev_i32_e32 v160, 4, v171
	v_bfe_u32 v170, v171, 5, 1
	s_ashr_i32 s5, s4, 1
	v_and_b32_e32 v2, 0xfffff0, v160
	v_lshlrev_b32_e32 v3, 1, v160
	v_and_b32_e32 v172, 31, v171
	s_and_b32 s18, s5, 0xffffffe0
	v_lshlrev_b32_e32 v48, 2, v170
	v_and_or_b32 v2, v3, 8, v2
	v_lshrrev_b32_e32 v3, 1, v160
	v_and_b32_e32 v4, 3, v160
	v_add_u32_e32 v162, 32, v160
	s_add_i32 s19, s18, s23
	v_sub_u32_e32 v0, v172, v48
	v_and_or_b32 v3, v3, 4, v4
	v_and_b32_e32 v4, 0xfffff0, v162
	v_lshlrev_b32_e32 v5, 1, v162
	v_add_u32_e32 v178, s19, v0
	v_lshlrev_b32_e32 v0, 3, v171
	v_and_or_b32 v4, v5, 8, v4
	v_and_b32_e32 v1, 0x78, v0
	v_lshrrev_b32_e32 v2, 1, v2
	v_bfe_u32 v0, v0, 5, 2
	v_lshrrev_b32_e32 v4, 1, v4
	v_or_b32_e32 v2, v2, v0
	v_lshlrev_b32_e32 v184, 1, v1
	v_or_b32_e32 v0, v4, v0
	v_lshlrev_b32_e32 v2, 9, v2
	v_lshlrev_b32_e32 v3, 6, v3
	v_and_b32_e32 v1, 48, v184
	v_lshlrev_b32_e32 v0, 9, v0
	v_or3_b32 v2, v2, v3, v1
	v_or3_b32 v0, v0, v3, v1
	v_add_u32_e32 v181, 0, v2
	v_add_u32_e32 v182, 0, v0
	ds_write_b128 v181, v[128:131]
	ds_write_b128 v182, v[132:135]
	v_ashrrev_i32_e32 v161, 31, v160
	v_lshlrev_b64 v[0:1], 8, v[160:161]
	s_mov_b64 s[24:25], 0x4000
	v_lshl_add_u64 v[2:3], v[0:1], 0, s[24:25]
	s_mov_b64 s[24:25], 0x6000
	v_lshl_add_u64 v[4:5], s[0:1], 0, v[2:3]
	v_lshl_add_u64 v[0:1], v[0:1], 0, s[24:25]
	v_lshl_add_u64 v[2:3], s[2:3], 0, v[2:3]
	v_lshl_add_u64 v[4:5], v[4:5], 0, v[184:185]
	v_lshl_add_u64 v[6:7], s[0:1], 0, v[0:1]
	v_lshl_add_u64 v[2:3], v[2:3], 0, v[184:185]
	v_lshl_add_u64 v[0:1], s[2:3], 0, v[0:1]
	v_lshl_add_u64 v[6:7], v[6:7], 0, v[184:185]
	global_load_dwordx4 v[32:35], v[4:5], off
	global_load_dwordx4 v[36:39], v[6:7], off
	v_lshl_add_u64 v[0:1], v[0:1], 0, v[184:185]
	global_load_dwordx4 v[40:43], v[2:3], off
	global_load_dwordx4 v[44:47], v[0:1], off
	v_lshlrev_b32_e32 v0, 3, v171
	v_lshlrev_b32_e32 v164, 4, v170
	v_and_b32_e32 v54, 0x70, v0
	v_lshlrev_b32_e32 v49, 7, v172
	v_xad_u32 v0, v164, v54, 0
	v_add_u32_e32 v180, v0, v49
	ds_read_b128 v[0:3], v180 offset:32768
	v_or_b32_e32 v4, 32, v164
	v_xad_u32 v4, v4, v54, 0
	v_add_u32_e32 v179, v4, v49
	ds_read_b128 v[50:53], v179 offset:32768
	v_or_b32_e32 v55, 64, v164
	v_xad_u32 v55, v55, v54, 0
	s_waitcnt vmcnt(11) lgkmcnt(1)
	v_mfma_f32_32x32x16_bf16 v[16:31], v[0:3], v[124:127], 0
	ds_read_b128 v[0:3], v180 offset:36864
	v_add_u32_e32 v165, v55, v49
	v_or_b32_e32 v55, 0x60, v164
	v_xad_u32 v54, v55, v54, 0
	v_add_u32_e32 v163, v54, v49
	s_sub_i32 s5, s19, 63
	s_cmpk_lt_u32 s5, 0x1fa2
	s_waitcnt vmcnt(10) lgkmcnt(1)
	v_mfma_f32_32x32x16_bf16 v[16:31], v[50:53], v[120:123], v[16:31]
	ds_read_b128 v[50:53], v179 offset:36864
	s_waitcnt lgkmcnt(1)
	v_mfma_f32_32x32x16_bf16 v[0:15], v[0:3], v[124:127], 0
	s_waitcnt lgkmcnt(0)
	v_mfma_f32_32x32x16_bf16 v[0:15], v[50:53], v[120:123], v[0:15]
	ds_read_b128 v[50:53], v165 offset:32768
	s_waitcnt vmcnt(9) lgkmcnt(0)
	v_mfma_f32_32x32x16_bf16 v[16:31], v[50:53], v[116:119], v[16:31]
	ds_read_b128 v[50:53], v165 offset:36864
	s_waitcnt lgkmcnt(0)
	v_mfma_f32_32x32x16_bf16 v[0:15], v[50:53], v[116:119], v[0:15]
	ds_read_b128 v[50:53], v163 offset:32768
	s_waitcnt vmcnt(8) lgkmcnt(0)
	v_mfma_f32_32x32x16_bf16 v[16:31], v[50:53], v[112:115], v[16:31]
	ds_read_b128 v[50:53], v163 offset:36864
	s_waitcnt lgkmcnt(0)
	v_mfma_f32_32x32x16_bf16 v[0:15], v[50:53], v[112:115], v[0:15]
	ds_read_b128 v[50:53], v180 offset:40960
	s_waitcnt vmcnt(7) lgkmcnt(0)
	v_mfma_f32_32x32x16_bf16 v[16:31], v[50:53], v[108:111], v[16:31]
	ds_read_b128 v[50:53], v180 offset:45056
	s_waitcnt lgkmcnt(0)
	v_mfma_f32_32x32x16_bf16 v[0:15], v[50:53], v[108:111], v[0:15]
	ds_read_b128 v[50:53], v179 offset:40960
	s_waitcnt vmcnt(6) lgkmcnt(0)
	v_mfma_f32_32x32x16_bf16 v[16:31], v[50:53], v[104:107], v[16:31]
	ds_read_b128 v[50:53], v179 offset:45056
	s_waitcnt lgkmcnt(0)
	v_mfma_f32_32x32x16_bf16 v[0:15], v[50:53], v[104:107], v[0:15]
	ds_read_b128 v[50:53], v165 offset:40960
	s_waitcnt vmcnt(5) lgkmcnt(0)
	v_mfma_f32_32x32x16_bf16 v[16:31], v[50:53], v[100:103], v[16:31]
	ds_read_b128 v[50:53], v165 offset:45056
	s_waitcnt lgkmcnt(0)
	v_mfma_f32_32x32x16_bf16 v[0:15], v[50:53], v[100:103], v[0:15]
	ds_read_b128 v[50:53], v163 offset:40960
	s_waitcnt vmcnt(4) lgkmcnt(0)
	v_mfma_f32_32x32x16_bf16 v[16:31], v[50:53], v[96:99], v[16:31]
	ds_read_b128 v[50:53], v163 offset:45056
	s_waitcnt lgkmcnt(0)
	v_mfma_f32_32x32x16_bf16 v[0:15], v[50:53], v[96:99], v[0:15]
	s_cbranch_scc1 .LBB0_192
	v_cmp_gt_u32_e32 vcc, s73, v178
	v_add_u32_e32 v49, 0xffffdfe0, v178
	s_nop 5
	v_cndmask_b32_e32 v16, v202, v16, vcc
	v_cmp_lt_u32_e32 vcc, s95, v49
	v_add_u32_e32 v49, 0xffffdfff, v178
	s_nop 0
	v_cndmask_b32_e32 v0, v202, v0, vcc
	v_cmp_lt_u32_e32 vcc, s95, v49
	v_add_u32_e32 v49, 0xffffdfdf, v178
	s_nop 0
	v_cndmask_b32_e32 v17, v202, v17, vcc
	v_cmp_lt_u32_e32 vcc, s95, v49
	v_add_u32_e32 v49, 0xffffdffe, v178
	s_nop 0
	v_cndmask_b32_e32 v1, v202, v1, vcc
	v_cmp_lt_u32_e32 vcc, s95, v49
	v_add_u32_e32 v49, 0xffffdfde, v178
	s_nop 0
	v_cndmask_b32_e32 v18, v202, v18, vcc
	v_cmp_lt_u32_e32 vcc, s95, v49
	v_add_u32_e32 v49, 0xffffdffd, v178
	s_nop 0
	v_cndmask_b32_e32 v2, v202, v2, vcc
	v_cmp_lt_u32_e32 vcc, s95, v49
	v_add_u32_e32 v49, 0xffffdfdd, v178
	s_nop 0
	v_cndmask_b32_e32 v19, v202, v19, vcc
	v_cmp_lt_u32_e32 vcc, s95, v49
	v_add_u32_e32 v49, 0xffffdff8, v178
	s_nop 0
	v_cndmask_b32_e32 v3, v202, v3, vcc
	v_cmp_lt_u32_e32 vcc, s95, v49
	v_add_u32_e32 v49, 0xffffdfd8, v178
	s_nop 0
	v_cndmask_b32_e32 v20, v202, v20, vcc
	v_cmp_lt_u32_e32 vcc, s95, v49
	v_add_u32_e32 v49, 0xffffdff7, v178
	s_nop 0
	v_cndmask_b32_e32 v4, v202, v4, vcc
	v_cmp_lt_u32_e32 vcc, s95, v49
	v_add_u32_e32 v49, 0xffffdfd7, v178
	s_nop 0
	v_cndmask_b32_e32 v21, v202, v21, vcc
	v_cmp_lt_u32_e32 vcc, s95, v49
	v_add_u32_e32 v49, 0xffffdff6, v178
	s_nop 0
	v_cndmask_b32_e32 v5, v202, v5, vcc
	v_cmp_lt_u32_e32 vcc, s95, v49
	v_add_u32_e32 v49, 0xffffdfd6, v178
	s_nop 0
	v_cndmask_b32_e32 v22, v202, v22, vcc
	v_cmp_lt_u32_e32 vcc, s95, v49
	v_add_u32_e32 v49, 0xffffdff5, v178
	s_nop 0
	v_cndmask_b32_e32 v6, v202, v6, vcc
	v_cmp_lt_u32_e32 vcc, s95, v49
	v_add_u32_e32 v49, 0xffffdfd5, v178
	s_nop 0
	v_cndmask_b32_e32 v23, v202, v23, vcc
	v_cmp_lt_u32_e32 vcc, s95, v49
	v_add_u32_e32 v49, 0xffffdff0, v178
	s_nop 0
	v_cndmask_b32_e32 v7, v202, v7, vcc
	v_cmp_lt_u32_e32 vcc, s95, v49
	v_add_u32_e32 v49, 0xffffdfd0, v178
	s_nop 0
	v_cndmask_b32_e32 v24, v202, v24, vcc
	v_cmp_lt_u32_e32 vcc, s95, v49
	v_add_u32_e32 v49, 0xffffdfef, v178
	s_nop 0
	v_cndmask_b32_e32 v8, v202, v8, vcc
	v_cmp_lt_u32_e32 vcc, s95, v49
	v_add_u32_e32 v49, 0xffffdfcf, v178
	s_nop 0
	v_cndmask_b32_e32 v25, v202, v25, vcc
	v_cmp_lt_u32_e32 vcc, s95, v49
	v_add_u32_e32 v49, 0xffffdfee, v178
	s_nop 0
	v_cndmask_b32_e32 v9, v202, v9, vcc
	v_cmp_lt_u32_e32 vcc, s95, v49
	v_add_u32_e32 v49, 0xffffdfce, v178
	s_nop 0
	v_cndmask_b32_e32 v26, v202, v26, vcc
	v_cmp_lt_u32_e32 vcc, s95, v49
	v_add_u32_e32 v49, 0xffffdfed, v178
	s_nop 0
	v_cndmask_b32_e32 v10, v202, v10, vcc
	v_cmp_lt_u32_e32 vcc, s95, v49
	v_add_u32_e32 v49, 0xffffdfcd, v178
	s_nop 0
	v_cndmask_b32_e32 v27, v202, v27, vcc
	v_cmp_lt_u32_e32 vcc, s95, v49
	v_add_u32_e32 v49, 0xffffdfe8, v178
	s_nop 0
	v_cndmask_b32_e32 v11, v202, v11, vcc
	v_cmp_lt_u32_e32 vcc, s95, v49
	v_add_u32_e32 v49, 0xffffdfc8, v178
	s_nop 0
	v_cndmask_b32_e32 v28, v202, v28, vcc
	v_cmp_lt_u32_e32 vcc, s95, v49
	v_add_u32_e32 v49, 0xffffdfe7, v178
	s_nop 0
	v_cndmask_b32_e32 v12, v202, v12, vcc
	v_cmp_lt_u32_e32 vcc, s95, v49
	v_add_u32_e32 v49, 0xffffdfc7, v178
	s_nop 0
	v_cndmask_b32_e32 v29, v202, v29, vcc
	v_cmp_lt_u32_e32 vcc, s95, v49
	v_add_u32_e32 v49, 0xffffdfe6, v178
	s_nop 0
	v_cndmask_b32_e32 v13, v202, v13, vcc
	v_cmp_lt_u32_e32 vcc, s95, v49
	v_add_u32_e32 v49, 0xffffdfc6, v178
	s_nop 0
	v_cndmask_b32_e32 v30, v202, v30, vcc
	v_cmp_lt_u32_e32 vcc, s95, v49
	v_add_u32_e32 v49, 0xffffdfe5, v178
	s_nop 0
	v_cndmask_b32_e32 v14, v202, v14, vcc
	v_cmp_lt_u32_e32 vcc, s95, v49
	v_add_u32_e32 v49, 0xffffdfc5, v178
	s_nop 0
	v_cndmask_b32_e32 v31, v202, v31, vcc
	v_cmp_lt_u32_e32 vcc, s95, v49
	s_nop 1
	v_cndmask_b32_e32 v15, v202, v15, vcc
.LBB0_192:
	s_and_b32 s4, s4, 0x3fffffc0
	v_and_b32_e32 v49, 63, v171
	s_lshl_b32 s4, s4, 2
	s_lshr_b32 s23, s23, 6
	s_add_i32 s4, s4, 0
	v_lshlrev_b32_e32 v50, 8, v160
	v_and_b32_e32 v51, 0x70, v171
	v_lshlrev_b32_e32 v52, 4, v49
	s_add_i32 s23, s23, 4
	s_add_i32 s26, s4, 0x10000
	v_bitop3_b32 v51, v184, v50, v51 bitop3:0xde
	v_lshlrev_b32_e32 v50, 3, v49
	v_and_b32_e32 v52, 0xc0, v52
	v_lshlrev_b32_e32 v53, 1, v49
	v_and_or_b32 v52, v50, 24, v52
	v_and_b32_e32 v53, 32, v53
	v_and_b32_e32 v50, 0x100, v50
	s_cmp_lg_u32 0, -1
	v_or3_b32 v50, v52, v53, v50
	s_cselect_b32 s4, 0, 0
	v_add_u32_e32 v173, s4, v50
	v_max_f32_e32 v50, v17, v17
	v_max_f32_e32 v52, v16, v16
	v_max_f32_e32 v50, v52, v50
	v_max3_f32 v50, v50, v18, v19
	v_max3_f32 v50, v50, v20, v21
	v_max3_f32 v50, v50, v22, v23
	v_max3_f32 v50, v50, v24, v25
	v_max3_f32 v50, v50, v26, v27
	v_max3_f32 v50, v50, v28, v29
	v_max3_f32 v50, v50, v30, v31
	v_max3_f32 v50, v50, v0, v1
	v_max3_f32 v50, v50, v2, v3
	v_max3_f32 v50, v50, v4, v5
	v_max3_f32 v50, v50, v6, v7
	v_max3_f32 v50, v50, v8, v9
	v_max3_f32 v50, v50, v10, v11
	v_max3_f32 v50, v50, v12, v13
	v_max3_f32 v50, v50, v14, v15
	v_mov_b32_e32 v52, v50
	s_nop 1
	v_permlane32_swap_b32_e32 v50, v52
	v_max_f32_e32 v52, v52, v52
	v_max_f32_e32 v50, v50, v50
	v_max_f32_e32 v50, v50, v52
	v_add_f32_e32 v52, 0x7149f2ca, v50
	v_mul_f32_e32 v52, 0x3db504f3, v52
	v_max_f32_e32 v50, 0xf149f2ca, v50
	v_cmp_ge_f32_e32 vcc, s87, v52
	v_sub_f32_e32 v52, 0xf149f2ca, v50
	s_add_i32 s24, s19, 0xffffe01f
	v_mul_f32_e32 v52, 0x3e0293ee, v52
	v_exp_f32_e32 v52, v52
	s_cmp_eq_u64 vcc, exec
	s_cselect_b64 vcc, -1, 0
	v_cndmask_b32_e32 v186, v50, v203, vcc
	v_mul_f32_e32 v50, 0xbe0293ee, v186
	v_cndmask_b32_e64 v183, v52, 1.0, vcc
	v_mov_b32_e32 v52, v50
	v_fmamk_f32 v16, v16, 0x3e0293ee, v50
	v_fmamk_f32 v17, v17, 0x3e0293ee, v50
	v_fmamk_f32 v18, v18, 0x3e0293ee, v50
	v_fmamk_f32 v19, v19, 0x3e0293ee, v50
	v_fmamk_f32 v20, v20, 0x3e0293ee, v50
	v_fmamk_f32 v21, v21, 0x3e0293ee, v50
	v_fmamk_f32 v22, v22, 0x3e0293ee, v50
	v_fmamk_f32 v23, v23, 0x3e0293ee, v50
	v_fmamk_f32 v24, v24, 0x3e0293ee, v50
	v_fmamk_f32 v25, v25, 0x3e0293ee, v50
	v_fmamk_f32 v26, v26, 0x3e0293ee, v50
	v_fmamk_f32 v27, v27, 0x3e0293ee, v50
	v_fmamk_f32 v28, v28, 0x3e0293ee, v50
	v_fmamk_f32 v29, v29, 0x3e0293ee, v50
	v_fmamk_f32 v30, v30, 0x3e0293ee, v50
	v_fmac_f32_e32 v52, 0x3e0293ee, v31
	v_lshl_add_u64 v[166:167], s[0:1], 0, v[184:185]
	s_add_i32 s0, s19, 0xffffdf45
	v_pk_fma_f32 v[156:157], v[0:1], s[90:91], v[50:51] op_sel_hi:[1,0,0]
	v_exp_f32_e32 v216, v16
	v_exp_f32_e32 v219, v17
	v_exp_f32_e32 v213, v18
	v_exp_f32_e32 v217, v19
	v_exp_f32_e32 v212, v20
	v_exp_f32_e32 v214, v21
	v_exp_f32_e32 v210, v22
	v_exp_f32_e32 v211, v23
	v_exp_f32_e32 v207, v24
	v_exp_f32_e32 v209, v25
	v_exp_f32_e32 v206, v26
	v_exp_f32_e32 v208, v27
	v_exp_f32_e32 v195, v28
	v_exp_f32_e32 v197, v29
	v_exp_f32_e32 v194, v30
	v_exp_f32_e32 v196, v52
	v_add_u32_e32 v0, s0, v172
	s_waitcnt vmcnt(0)
	v_lshlrev_b32_e32 v176, 4, v187
	v_and_b32_e32 v51, 0x70, v176
	v_and_b32_e32 v176, 0x80, v176
	v_lshlrev_b32_e32 v176, 6, v176
	v_or_b32_e32 v176, v176, v51
	v_lshrrev_b32_e32 v51, 1, v187
	v_and_b32_e32 v51, 0x70, v51
	v_xor_b32_e32 v176, v176, v51
	v_lshrrev_b32_e32 v51, 4, v187
	v_lshl_add_u32 v176, v51, 7, v176
	v_cmp_gt_u32_e64 s[4:5], 32, v49
	v_lshl_add_u32 v174, v48, 2, s26
	v_sub_u32_e32 v188, v0, v48
	v_mov_b32_e32 v48, v185
	v_mov_b32_e32 v49, v185
	v_pk_fma_f32 v[146:147], v[14:15], s[90:91], v[50:51] op_sel_hi:[1,0,0]
	v_pk_fma_f32 v[152:153], v[12:13], s[90:91], v[50:51] op_sel_hi:[1,0,0]
	v_pk_fma_f32 v[158:159], v[10:11], s[90:91], v[50:51] op_sel_hi:[1,0,0]
	v_pk_fma_f32 v[144:145], v[8:9], s[90:91], v[50:51] op_sel_hi:[1,0,0]
	v_pk_fma_f32 v[148:149], v[6:7], s[90:91], v[50:51] op_sel_hi:[1,0,0]
	v_pk_fma_f32 v[150:151], v[4:5], s[90:91], v[50:51] op_sel_hi:[1,0,0]
	v_pk_fma_f32 v[154:155], v[2:3], s[90:91], v[50:51] op_sel_hi:[1,0,0]
	s_waitcnt vmcnt(3)
	ds_write_b128 v181, v[32:35] offset:16384
	s_waitcnt vmcnt(2)
	ds_write_b128 v182, v[36:39] offset:16384
	s_waitcnt vmcnt(1)
	ds_write_b128 v176, v[40:43] offset:49152
	s_waitcnt vmcnt(0)
	ds_write_b128 v176, v[44:47] offset:53248
	v_mov_b32_e32 v50, v185
	v_mov_b32_e32 v51, v185
	v_mov_b32_e32 v52, v185
	v_mov_b32_e32 v53, v185
	v_mov_b32_e32 v54, v185
	v_mov_b32_e32 v55, v185
	v_mov_b32_e32 v56, v185
	v_mov_b32_e32 v57, v185
	v_mov_b32_e32 v58, v185
	v_mov_b32_e32 v59, v185
	v_mov_b32_e32 v60, v185
	v_mov_b32_e32 v61, v185
	v_mov_b32_e32 v62, v185
	v_mov_b32_e32 v63, v185
	v_mov_b64_e32 v[32:33], v[48:49]
	v_mov_b64_e32 v[16:17], v[48:49]
	v_mov_b64_e32 v[0:1], v[48:49]
	s_mov_b32 s25, 2
	v_lshl_add_u64 v[168:169], s[2:3], 0, v[184:185]
	v_lshl_add_u32 v175, v172, 2, s26
	v_mov_b32_e32 v177, 0
	s_movk_i32 s26, 0x7f
	v_mov_b64_e32 v[34:35], v[50:51]
	v_mov_b64_e32 v[36:37], v[52:53]
	v_mov_b64_e32 v[38:39], v[54:55]
	v_mov_b64_e32 v[40:41], v[56:57]
	v_mov_b64_e32 v[42:43], v[58:59]
	v_mov_b64_e32 v[44:45], v[60:61]
	v_mov_b64_e32 v[46:47], v[62:63]
	v_mov_b64_e32 v[18:19], v[50:51]
	v_mov_b64_e32 v[20:21], v[52:53]
	v_mov_b64_e32 v[22:23], v[54:55]
	v_mov_b64_e32 v[24:25], v[56:57]
	v_mov_b64_e32 v[26:27], v[58:59]
	v_mov_b64_e32 v[28:29], v[60:61]
	v_mov_b64_e32 v[30:31], v[62:63]
	v_mov_b64_e32 v[2:3], v[50:51]
	v_mov_b64_e32 v[4:5], v[52:53]
	v_mov_b64_e32 v[6:7], v[54:55]
	v_mov_b64_e32 v[8:9], v[56:57]
	v_mov_b64_e32 v[10:11], v[58:59]
	v_mov_b64_e32 v[12:13], v[60:61]
	v_mov_b64_e32 v[14:15], v[62:63]
	s_waitcnt lgkmcnt(0)
	s_barrier
.LBB0_193:
	ds_read_b128 v[64:67], v180 offset:49152
	ds_read_b128 v[68:71], v180 offset:53248
	ds_read_b128 v[128:131], v179 offset:49152
	s_waitcnt vmcnt(2)
	ds_read_b128 v[132:135], v179 offset:53248
	ds_read_b128 v[248:251], v165 offset:49152
	ds_read_b128 v[252:255], v165 offset:53248
	s_waitcnt vmcnt(1)
	v_exp_f32_e32 v136, v144
	v_add_f32_e32 v144, 0, v216
	s_waitcnt lgkmcnt(5)
	v_mfma_f32_32x32x16_bf16 v[80:95], v[64:67], v[124:127], 0
	v_add_f32_e32 v144, v219, v144
	v_add_f32_e32 v144, v213, v144
	v_add_f32_e32 v144, v217, v144
	v_add_f32_e32 v144, v212, v144
	v_add_f32_e32 v144, v214, v144
	v_add_f32_e32 v144, v210, v144
	v_add_f32_e32 v144, v211, v144
	s_waitcnt lgkmcnt(4)
	v_mfma_f32_32x32x16_bf16 v[64:79], v[68:71], v[124:127], 0
	v_add_f32_e32 v144, v207, v144
	v_add_f32_e32 v144, v209, v144
	v_add_f32_e32 v144, v206, v144
	v_add_f32_e32 v144, v208, v144
	v_add_f32_e32 v144, v195, v144
	v_add_f32_e32 v144, v197, v144
	v_add_f32_e32 v144, v194, v144
	s_waitcnt lgkmcnt(3)
	v_mfma_f32_32x32x16_bf16 v[80:95], v[128:131], v[120:123], v[80:95]
	v_add_f32_e32 v144, v196, v144
	v_exp_f32_e32 v137, v145
	v_exp_f32_e32 v138, v158
	v_exp_f32_e32 v139, v159
	s_waitcnt vmcnt(0)
	v_exp_f32_e32 v140, v152
	v_exp_f32_e32 v141, v153
	v_exp_f32_e32 v142, v146
	s_waitcnt lgkmcnt(2)
	v_mfma_f32_32x32x16_bf16 v[64:79], v[132:135], v[120:123], v[64:79]
	ds_read_b128 v[128:131], v163 offset:49152
	ds_read_b128 v[132:135], v163 offset:53248
	v_exp_f32_e32 v143, v147
	s_sub_i32 s0, s26, 63
	s_waitcnt lgkmcnt(3)
	v_mfma_f32_32x32x16_bf16 v[80:95], v[248:251], v[116:119], v[80:95]
	s_waitcnt lgkmcnt(2)
	v_mfma_f32_32x32x16_bf16 v[64:79], v[252:255], v[116:119], v[64:79]
	ds_read_b128 v[248:251], v180 offset:57344
	ds_read_b128 v[252:255], v180 offset:61440
	s_waitcnt lgkmcnt(3)
	v_mfma_f32_32x32x16_bf16 v[80:95], v[128:131], v[112:115], v[80:95]
	s_waitcnt lgkmcnt(2)
	v_mfma_f32_32x32x16_bf16 v[64:79], v[132:135], v[112:115], v[64:79]
	ds_read_b128 v[128:131], v179 offset:57344
	ds_read_b128 v[132:135], v179 offset:61440
	s_waitcnt lgkmcnt(3)
	v_mfma_f32_32x32x16_bf16 v[80:95], v[248:251], v[108:111], v[80:95]
	s_waitcnt lgkmcnt(2)
	v_mfma_f32_32x32x16_bf16 v[64:79], v[252:255], v[108:111], v[64:79]
	ds_read_b128 v[248:251], v165 offset:57344
	ds_read_b128 v[252:255], v165 offset:61440
	s_waitcnt lgkmcnt(3)
	v_mfma_f32_32x32x16_bf16 v[80:95], v[128:131], v[104:107], v[80:95]
	s_waitcnt lgkmcnt(2)
	v_mfma_f32_32x32x16_bf16 v[64:79], v[132:135], v[104:107], v[64:79]
	ds_read_b128 v[128:131], v163 offset:57344
	ds_read_b128 v[132:135], v163 offset:61440
	s_waitcnt lgkmcnt(3)
	v_mfma_f32_32x32x16_bf16 v[80:95], v[248:251], v[100:103], v[80:95]
	s_waitcnt lgkmcnt(2)
	v_mfma_f32_32x32x16_bf16 v[64:79], v[252:255], v[100:103], v[64:79]
	s_waitcnt lgkmcnt(1)
	v_mfma_f32_32x32x16_bf16 v[80:95], v[128:131], v[96:99], v[80:95]
	v_exp_f32_e32 v128, v156
	v_exp_f32_e32 v129, v157
	v_exp_f32_e32 v130, v154
	v_exp_f32_e32 v131, v155
	v_add_f32_e32 v144, v128, v144
	v_add_f32_e32 v144, v129, v144
	v_add_f32_e32 v144, v130, v144
	s_waitcnt lgkmcnt(0)
	v_mfma_f32_32x32x16_bf16 v[64:79], v[132:135], v[96:99], v[64:79]
	v_exp_f32_e32 v132, v150
	v_exp_f32_e32 v133, v151
	v_exp_f32_e32 v134, v148
	v_exp_f32_e32 v135, v149
	v_add_f32_e32 v144, v131, v144
	v_add_f32_e32 v144, v132, v144
	v_add_f32_e32 v144, v133, v144
	v_add_f32_e32 v144, v134, v144
	v_add_f32_e32 v144, v135, v144
	v_add_f32_e32 v144, v136, v144
	v_add_f32_e32 v144, v137, v144
	v_add_f32_e32 v144, v138, v144
	v_add_f32_e32 v144, v139, v144
	v_add_f32_e32 v144, v140, v144
	v_add_f32_e32 v144, v141, v144
	v_add_f32_e32 v144, v142, v144
	v_add_f32_e32 v190, v143, v144
	v_mov_b32_e32 v191, v190
	s_nop 1
	v_permlane32_swap_b32_e32 v190, v191
	s_nop 0
	v_cvt_pk_bf16_f32 v144, v216, v219
	s_nop 0
	v_cvt_pk_bf16_f32 v145, v213, v217
	s_nop 0
	v_cvt_pk_bf16_f32 v146, v212, v214
	s_nop 0
	v_cvt_pk_bf16_f32 v147, v210, v211
	s_nop 0
	v_cvt_pk_bf16_f32 v148, v207, v209
	s_nop 0
	v_cvt_pk_bf16_f32 v149, v206, v208
	s_nop 0
	v_cvt_pk_bf16_f32 v150, v195, v197
	s_nop 0
	v_cvt_pk_bf16_f32 v151, v194, v196
	s_nop 0
	v_cvt_pk_bf16_f32 v152, v128, v129
	s_nop 0
	v_cvt_pk_bf16_f32 v153, v130, v131
	s_nop 0
	v_cvt_pk_bf16_f32 v154, v132, v133
	s_nop 0
	v_cvt_pk_bf16_f32 v155, v134, v135
	s_nop 0
	v_cvt_pk_bf16_f32 v156, v136, v137
	s_nop 0
	v_cvt_pk_bf16_f32 v157, v138, v139
	s_nop 0
	v_cvt_pk_bf16_f32 v158, v140, v141
	s_nop 0
	v_cvt_pk_bf16_f32 v159, v142, v143
	s_nop 0
	v_permlane32_swap_b32_e32 v144, v146
	v_permlane32_swap_b32_e32 v145, v147
	v_permlane32_swap_b32_e32 v148, v150
	v_permlane32_swap_b32_e32 v149, v151
	v_permlane32_swap_b32_e32 v152, v154
	v_permlane32_swap_b32_e32 v153, v155
	v_permlane32_swap_b32_e32 v156, v158
	v_permlane32_swap_b32_e32 v157, v159
	v_add_u32_e32 v192, s26, v160
	v_add_u32_e32 v128, 1, v192
	v_add_u32_e32 v130, 33, v192
	v_ashrrev_i32_e32 v129, 31, v128
	v_ashrrev_i32_e32 v131, 31, v130
	v_lshlrev_b64 v[136:137], 8, v[128:129]
	v_lshlrev_b64 v[138:139], 8, v[130:131]
	v_lshl_add_u64 v[128:129], v[166:167], 0, v[136:137]
	v_lshl_add_u64 v[132:133], v[166:167], 0, v[138:139]
	v_lshl_add_u64 v[136:137], v[168:169], 0, v[136:137]
	v_lshl_add_u64 v[140:141], v[168:169], 0, v[138:139]
	global_load_dwordx4 v[128:131], v[128:129], off
	s_nop 0
	global_load_dwordx4 v[132:135], v[132:133], off
	s_nop 0
	global_load_dwordx4 v[136:139], v[136:137], off
	s_nop 0
	global_load_dwordx4 v[140:143], v[140:141], off
	ds_read_b64_tr_b16 v[194:195], v173 offset:0
	ds_read_b64_tr_b16 v[196:197], v173 offset:0x800
	ds_read_b64_tr_b16 v[206:207], v173 offset:0x1000
	ds_read_b64_tr_b16 v[208:209], v173 offset:0x1800
	ds_read_b64_tr_b16 v[210:211], v173 offset:0x2000
	ds_read_b64_tr_b16 v[212:213], v173 offset:0x2800
	ds_read_b64_tr_b16 v[214:215], v173 offset:0x3000
	ds_read_b64_tr_b16 v[216:217], v173 offset:0x3800
	s_waitcnt lgkmcnt(0)
	s_nop 0
	v_mfma_f32_32x32x16_bf16 v[48:63], v[144:147], v[194:197], v[48:63]
	ds_read_b64_tr_b16 v[194:195], v173 offset:0x200
	ds_read_b64_tr_b16 v[196:197], v173 offset:0xa00
	v_mfma_f32_32x32x16_bf16 v[48:63], v[148:151], v[206:209], v[48:63]
	ds_read_b64_tr_b16 v[206:207], v173 offset:0x1200
	ds_read_b64_tr_b16 v[208:209], v173 offset:0x1a00
	v_mfma_f32_32x32x16_bf16 v[48:63], v[152:155], v[210:213], v[48:63]
	ds_read_b64_tr_b16 v[210:211], v173 offset:0x2200
	ds_read_b64_tr_b16 v[212:213], v173 offset:0x2a00
	v_mfma_f32_32x32x16_bf16 v[48:63], v[156:159], v[214:217], v[48:63]
	ds_read_b64_tr_b16 v[214:215], v173 offset:0x3200
	ds_read_b64_tr_b16 v[216:217], v173 offset:0x3a00
	s_waitcnt lgkmcnt(0)
	v_mfma_f32_32x32x16_bf16 v[32:47], v[144:147], v[194:197], v[32:47]
	ds_read_b64_tr_b16 v[194:195], v173 offset:0x400
	ds_read_b64_tr_b16 v[196:197], v173 offset:0xc00
	v_mfma_f32_32x32x16_bf16 v[32:47], v[148:151], v[206:209], v[32:47]
	ds_read_b64_tr_b16 v[206:207], v173 offset:0x1400
	ds_read_b64_tr_b16 v[208:209], v173 offset:0x1c00
	v_mfma_f32_32x32x16_bf16 v[32:47], v[152:155], v[210:213], v[32:47]
	ds_read_b64_tr_b16 v[210:211], v173 offset:0x2400
	ds_read_b64_tr_b16 v[212:213], v173 offset:0x2c00
	v_mfma_f32_32x32x16_bf16 v[32:47], v[156:159], v[214:217], v[32:47]
	ds_read_b64_tr_b16 v[214:215], v173 offset:0x3400
	ds_read_b64_tr_b16 v[216:217], v173 offset:0x3c00
	s_waitcnt lgkmcnt(0)
	v_mfma_f32_32x32x16_bf16 v[16:31], v[144:147], v[194:197], v[16:31]
	ds_read_b64_tr_b16 v[194:195], v173 offset:0x600
	ds_read_b64_tr_b16 v[196:197], v173 offset:0xe00
	v_mfma_f32_32x32x16_bf16 v[16:31], v[148:151], v[206:209], v[16:31]
	ds_read_b64_tr_b16 v[206:207], v173 offset:0x1600
	ds_read_b64_tr_b16 v[208:209], v173 offset:0x1e00
	v_mfma_f32_32x32x16_bf16 v[16:31], v[152:155], v[210:213], v[16:31]
	ds_read_b64_tr_b16 v[210:211], v173 offset:0x2600
	ds_read_b64_tr_b16 v[212:213], v173 offset:0x2e00
	v_mfma_f32_32x32x16_bf16 v[16:31], v[156:159], v[214:217], v[16:31]
	ds_read_b64_tr_b16 v[214:215], v173 offset:0x3600
	ds_read_b64_tr_b16 v[216:217], v173 offset:0x3e00
	s_waitcnt lgkmcnt(0)
	v_mfma_f32_32x32x16_bf16 v[0:15], v[144:147], v[194:197], v[0:15]
	s_cmp_le_i32 s26, s19
	s_cselect_b64 s[2:3], -1, 0
	s_cmp_gt_i32 s0, s24
	s_cselect_b64 s[0:1], -1, 0
	s_and_b64 s[0:1], s[2:3], s[0:1]
	s_and_b64 vcc, exec, s[0:1]
	v_mfma_f32_32x32x16_bf16 v[0:15], v[148:151], v[206:209], v[0:15]
	v_mfma_f32_32x32x16_bf16 v[0:15], v[152:155], v[210:213], v[0:15]
	v_mfma_f32_32x32x16_bf16 v[0:15], v[156:159], v[214:217], v[0:15]
	s_waitcnt vmcnt(0)
	ds_write_b128 v176, v[136:139] offset:32768
	ds_write_b128 v176, v[140:143] offset:36864
	s_cbranch_vccnz .LBB0_195
	v_add_u32_e32 v144, 0x207b, v188
	v_cmp_gt_u32_e32 vcc, s73, v144
	v_add_u32_e32 v144, 0x5b, v188
	s_nop 0
	v_cndmask_b32_e32 v80, v202, v80, vcc
	v_cmp_lt_u32_e32 vcc, s95, v144
	v_add_u32_e32 v144, 0x7a, v188
	s_nop 0
	v_cndmask_b32_e32 v64, v202, v64, vcc
	v_cmp_lt_u32_e32 vcc, s95, v144
	v_add_u32_e32 v144, 0x5a, v188
	s_nop 0
	v_cndmask_b32_e32 v81, v202, v81, vcc
	v_cmp_lt_u32_e32 vcc, s95, v144
	v_add_u32_e32 v144, 0x79, v188
	s_nop 0
	v_cndmask_b32_e32 v65, v202, v65, vcc
	v_cmp_lt_u32_e32 vcc, s95, v144
	v_add_u32_e32 v144, 0x59, v188
	s_nop 0
	v_cndmask_b32_e32 v82, v202, v82, vcc
	v_cmp_lt_u32_e32 vcc, s95, v144
	v_add_u32_e32 v144, 0x78, v188
	s_nop 0
	v_cndmask_b32_e32 v66, v202, v66, vcc
	v_cmp_lt_u32_e32 vcc, s95, v144
	v_add_u32_e32 v144, 0x58, v188
	s_nop 0
	v_cndmask_b32_e32 v83, v202, v83, vcc
	v_cmp_lt_u32_e32 vcc, s95, v144
	v_add_u32_e32 v144, 0x73, v188
	s_nop 0
	v_cndmask_b32_e32 v67, v202, v67, vcc
	v_cmp_lt_u32_e32 vcc, s95, v144
	v_add_u32_e32 v144, 0x53, v188
	s_nop 0
	v_cndmask_b32_e32 v84, v202, v84, vcc
	v_cmp_lt_u32_e32 vcc, s95, v144
	v_add_u32_e32 v144, 0x72, v188
	s_nop 0
	v_cndmask_b32_e32 v68, v202, v68, vcc
	v_cmp_lt_u32_e32 vcc, s95, v144
	v_add_u32_e32 v144, 0x52, v188
	s_nop 0
	v_cndmask_b32_e32 v85, v202, v85, vcc
	v_cmp_lt_u32_e32 vcc, s95, v144
	v_add_u32_e32 v144, 0x71, v188
	s_nop 0
	v_cndmask_b32_e32 v69, v202, v69, vcc
	v_cmp_lt_u32_e32 vcc, s95, v144
	v_add_u32_e32 v144, 0x51, v188
	s_nop 0
	v_cndmask_b32_e32 v86, v202, v86, vcc
	v_cmp_lt_u32_e32 vcc, s95, v144
	v_add_u32_e32 v144, 0x70, v188
	s_nop 0
	v_cndmask_b32_e32 v70, v202, v70, vcc
	v_cmp_lt_u32_e32 vcc, s95, v144
	v_add_u32_e32 v144, 0x50, v188
	s_nop 0
	v_cndmask_b32_e32 v87, v202, v87, vcc
	v_cmp_lt_u32_e32 vcc, s95, v144
	v_add_u32_e32 v144, 0x6b, v188
	s_nop 0
	v_cndmask_b32_e32 v71, v202, v71, vcc
	v_cmp_lt_u32_e32 vcc, s95, v144
	v_add_u32_e32 v144, 0x4b, v188
	s_nop 0
	v_cndmask_b32_e32 v88, v202, v88, vcc
	v_cmp_lt_u32_e32 vcc, s95, v144
	v_add_u32_e32 v144, 0x6a, v188
	s_nop 0
	v_cndmask_b32_e32 v72, v202, v72, vcc
	v_cmp_lt_u32_e32 vcc, s95, v144
	v_add_u32_e32 v144, 0x4a, v188
	s_nop 0
	v_cndmask_b32_e32 v89, v202, v89, vcc
	v_cmp_lt_u32_e32 vcc, s95, v144
	v_add_u32_e32 v144, 0x69, v188
	s_nop 0
	v_cndmask_b32_e32 v73, v202, v73, vcc
	v_cmp_lt_u32_e32 vcc, s95, v144
	v_add_u32_e32 v144, 0x49, v188
	s_nop 0
	v_cndmask_b32_e32 v90, v202, v90, vcc
	v_cmp_lt_u32_e32 vcc, s95, v144
	v_add_u32_e32 v144, 0x68, v188
	s_nop 0
	v_cndmask_b32_e32 v74, v202, v74, vcc
	v_cmp_lt_u32_e32 vcc, s95, v144
	v_add_u32_e32 v144, 0x48, v188
	s_nop 0
	v_cndmask_b32_e32 v91, v202, v91, vcc
	v_cmp_lt_u32_e32 vcc, s95, v144
	v_add_u32_e32 v144, 0x63, v188
	s_nop 0
	v_cndmask_b32_e32 v75, v202, v75, vcc
	v_cmp_lt_u32_e32 vcc, s95, v144
	v_add_u32_e32 v144, 0x43, v188
	s_nop 0
	v_cndmask_b32_e32 v92, v202, v92, vcc
	v_cmp_lt_u32_e32 vcc, s95, v144
	v_add_u32_e32 v144, 0x62, v188
	s_nop 0
	v_cndmask_b32_e32 v76, v202, v76, vcc
	v_cmp_lt_u32_e32 vcc, s95, v144
	v_add_u32_e32 v144, 0x42, v188
	s_nop 0
	v_cndmask_b32_e32 v93, v202, v93, vcc
	v_cmp_lt_u32_e32 vcc, s95, v144
	v_add_u32_e32 v144, 0x61, v188
	s_nop 0
	v_cndmask_b32_e32 v77, v202, v77, vcc
	v_cmp_lt_u32_e32 vcc, s95, v144
	v_add_u32_e32 v144, 0x41, v188
	s_nop 0
	v_cndmask_b32_e32 v94, v202, v94, vcc
	v_cmp_lt_u32_e32 vcc, s95, v144
	v_add_u32_e32 v144, 0x60, v188
	s_nop 0
	v_cndmask_b32_e32 v78, v202, v78, vcc
	v_cmp_lt_u32_e32 vcc, s95, v144
	v_add_u32_e32 v144, 64, v188
	s_nop 0
	v_cndmask_b32_e32 v95, v202, v95, vcc
	v_cmp_lt_u32_e32 vcc, s95, v144
	s_nop 1
	v_cndmask_b32_e32 v79, v202, v79, vcc

.Lhs2_top:
	ds_read_b128 v[64:67], v180 offset:32768
	ds_read_b128 v[68:71], v180 offset:36864
	ds_read_b128 v[218:221], v179 offset:32768
	ds_read_b128 v[222:225], v179 offset:36864
	ds_read_b128 v[248:251], v165 offset:32768
	ds_read_b128 v[252:255], v165 offset:36864
	v_exp_f32_e32 v211, v211
	v_exp_f32_e32 v212, v212
	s_waitcnt lgkmcnt(5)
	v_mfma_f32_32x32x16_bf16 v[80:95], v[64:67], v[124:127], 0
	v_exp_f32_e32 v213, v213
	v_exp_f32_e32 v214, v214
	v_exp_f32_e32 v196, v196
	v_exp_f32_e32 v197, v197
	v_exp_f32_e32 v206, v206
	v_exp_f32_e32 v207, v207
	v_exp_f32_e32 v208, v208
	s_waitcnt lgkmcnt(4)
	v_mfma_f32_32x32x16_bf16 v[64:79], v[68:71], v[124:127], 0
	v_exp_f32_e32 v209, v209
	v_exp_f32_e32 v210, v210
	v_exp_f32_e32 v195, v195
	v_exp_f32_e32 v216, v216
	v_exp_f32_e32 v217, v217
	v_exp_f32_e32 v194, v194
	s_waitcnt lgkmcnt(3)
	v_mfma_f32_32x32x16_bf16 v[80:95], v[218:221], v[120:123], v[80:95]
	s_waitcnt lgkmcnt(2)
	v_mfma_f32_32x32x16_bf16 v[64:79], v[222:225], v[120:123], v[64:79]
	ds_read_b128 v[218:221], v163 offset:32768
	ds_read_b128 v[222:225], v163 offset:36864
	s_waitcnt lgkmcnt(3)
	v_mfma_f32_32x32x16_bf16 v[80:95], v[248:251], v[116:119], v[80:95]
	s_waitcnt lgkmcnt(2)
	v_mfma_f32_32x32x16_bf16 v[64:79], v[252:255], v[116:119], v[64:79]
	ds_read_b128 v[248:251], v180 offset:40960
	ds_read_b128 v[252:255], v180 offset:45056
	s_waitcnt lgkmcnt(3)
	v_mfma_f32_32x32x16_bf16 v[80:95], v[218:221], v[112:115], v[80:95]
	s_waitcnt lgkmcnt(2)
	v_mfma_f32_32x32x16_bf16 v[64:79], v[222:225], v[112:115], v[64:79]
	ds_read_b128 v[218:221], v179 offset:40960
	ds_read_b128 v[222:225], v179 offset:45056
	s_waitcnt lgkmcnt(3)
	v_mfma_f32_32x32x16_bf16 v[80:95], v[248:251], v[108:111], v[80:95]
	s_waitcnt lgkmcnt(2)
	v_mfma_f32_32x32x16_bf16 v[64:79], v[252:255], v[108:111], v[64:79]
	ds_read_b128 v[248:251], v165 offset:40960
	ds_read_b128 v[252:255], v165 offset:45056
	s_waitcnt lgkmcnt(3)
	v_mfma_f32_32x32x16_bf16 v[80:95], v[218:221], v[104:107], v[80:95]
	s_waitcnt lgkmcnt(2)
	v_mfma_f32_32x32x16_bf16 v[64:79], v[222:225], v[104:107], v[64:79]
	ds_read_b128 v[218:221], v163 offset:40960
	ds_read_b128 v[222:225], v163 offset:45056
	s_waitcnt lgkmcnt(3)
	v_mfma_f32_32x32x16_bf16 v[80:95], v[248:251], v[100:103], v[80:95]
	s_waitcnt lgkmcnt(2)
	v_mfma_f32_32x32x16_bf16 v[64:79], v[252:255], v[100:103], v[64:79]
	s_waitcnt lgkmcnt(1)
	v_mfma_f32_32x32x16_bf16 v[80:95], v[218:221], v[96:99], v[80:95]
	v_exp_f32_e32 v219, v215
	v_add_f32_e32 v215, 0, v144
	v_add_f32_e32 v215, v159, v215
	v_add_f32_e32 v215, v145, v215
	v_add_f32_e32 v215, v158, v215
	v_add_f32_e32 v215, v146, v215
	v_add_f32_e32 v215, v157, v215
	v_add_f32_e32 v215, v147, v215
	v_add_f32_e32 v215, v156, v215
	v_add_f32_e32 v215, v148, v215
	v_add_f32_e32 v215, v155, v215
	v_add_f32_e32 v215, v149, v215
	v_add_f32_e32 v215, v154, v215
	v_add_f32_e32 v215, v150, v215
	v_add_f32_e32 v215, v153, v215
	v_add_f32_e32 v215, v151, v215
	v_add_f32_e32 v215, v152, v215
	v_add_f32_e32 v215, v211, v215
	v_add_f32_e32 v215, v212, v215
	v_add_f32_e32 v215, v213, v215
	v_add_f32_e32 v215, v214, v215
	v_add_f32_e32 v215, v219, v215
	v_add_f32_e32 v215, v196, v215
	v_add_f32_e32 v215, v197, v215
	v_add_f32_e32 v215, v206, v215
	v_add_f32_e32 v215, v207, v215
	v_add_f32_e32 v215, v208, v215
	s_waitcnt lgkmcnt(0)
	v_mfma_f32_32x32x16_bf16 v[64:79], v[222:225], v[96:99], v[64:79]
	v_add_f32_e32 v215, v209, v215
	v_add_f32_e32 v215, v210, v215
	v_add_f32_e32 v215, v195, v215
	v_add_f32_e32 v215, v216, v215
	v_add_f32_e32 v215, v217, v215
	v_add_f32_e32 v215, v194, v215
	v_mov_b32_e32 v218, v215
	s_nop 0
	v_cvt_pk_bf16_f32 v144, v144, v159
	s_nop 0
	v_cvt_pk_bf16_f32 v145, v145, v158
	s_nop 0
	v_cvt_pk_bf16_f32 v146, v146, v157
	s_nop 0
	v_cvt_pk_bf16_f32 v147, v147, v156
	s_nop 0
	v_cvt_pk_bf16_f32 v148, v148, v155
	s_nop 0
	v_cvt_pk_bf16_f32 v149, v149, v154
	s_nop 0
	v_cvt_pk_bf16_f32 v150, v150, v153
	s_nop 0
	v_cvt_pk_bf16_f32 v151, v151, v152
	s_nop 0
	v_cvt_pk_bf16_f32 v152, v211, v212
	s_nop 0
	v_cvt_pk_bf16_f32 v153, v213, v214
	s_nop 0
	v_cvt_pk_bf16_f32 v154, v219, v196
	s_nop 0
	v_cvt_pk_bf16_f32 v155, v197, v206
	s_nop 0
	v_cvt_pk_bf16_f32 v156, v207, v208
	s_nop 0
	v_cvt_pk_bf16_f32 v157, v209, v210
	s_nop 0
	v_cvt_pk_bf16_f32 v158, v195, v216
	s_nop 0
	v_cvt_pk_bf16_f32 v159, v217, v194
	s_nop 1
	v_permlane32_swap_b32_e32 v215, v218
	v_permlane32_swap_b32_e32 v144, v146
	v_permlane32_swap_b32_e32 v145, v147
	v_permlane32_swap_b32_e32 v148, v150
	v_permlane32_swap_b32_e32 v149, v151
	v_permlane32_swap_b32_e32 v152, v154
	v_permlane32_swap_b32_e32 v153, v155
	v_permlane32_swap_b32_e32 v156, v158
	v_permlane32_swap_b32_e32 v157, v159
	s_add_i32 s0, s25, 1
	s_cmp_lt_u32 s0, s23
	s_cselect_b64 s[2:3], -1, 0
	s_cmp_ge_u32 s0, s23
	s_cbranch_scc1 .LBB0_201
	v_add_u32_e32 v128, 0x41, v192
	v_add_u32_e32 v130, 0x61, v192
	v_ashrrev_i32_e32 v129, 31, v128
	v_ashrrev_i32_e32 v131, 31, v130
	v_lshlrev_b64 v[136:137], 8, v[128:129]
	v_lshlrev_b64 v[138:139], 8, v[130:131]
	v_lshl_add_u64 v[128:129], v[166:167], 0, v[136:137]
	v_lshl_add_u64 v[132:133], v[166:167], 0, v[138:139]
	v_lshl_add_u64 v[136:137], v[168:169], 0, v[136:137]
	v_lshl_add_u64 v[140:141], v[168:169], 0, v[138:139]
	global_load_dwordx4 v[128:131], v[128:129], off
	s_nop 0
	global_load_dwordx4 v[132:135], v[132:133], off
	s_nop 0
	global_load_dwordx4 v[136:139], v[136:137], off
	s_nop 0
	global_load_dwordx4 v[140:143], v[140:141], off
.LBB0_201:
	ds_read_b64_tr_b16 v[194:195], v173 offset:0x4000
	ds_read_b64_tr_b16 v[196:197], v173 offset:0x4800
	ds_read_b64_tr_b16 v[206:207], v173 offset:0x5000
	ds_read_b64_tr_b16 v[208:209], v173 offset:0x5800
	ds_read_b64_tr_b16 v[210:211], v173 offset:0x6000
	ds_read_b64_tr_b16 v[212:213], v173 offset:0x6800
	ds_read_b64_tr_b16 v[220:221], v173 offset:0x7000
	ds_read_b64_tr_b16 v[222:223], v173 offset:0x7800
	s_waitcnt lgkmcnt(0)
	s_add_i32 s0, s26, 64
	s_add_i32 s27, s26, 1
	v_mfma_f32_32x32x16_bf16 v[48:63], v[144:147], v[194:197], v[48:63]
	ds_read_b64_tr_b16 v[194:195], v173 offset:0x4200
	ds_read_b64_tr_b16 v[196:197], v173 offset:0x4a00
	v_mfma_f32_32x32x16_bf16 v[48:63], v[148:151], v[206:209], v[48:63]
	ds_read_b64_tr_b16 v[206:207], v173 offset:0x5200
	ds_read_b64_tr_b16 v[208:209], v173 offset:0x5a00
	v_mfma_f32_32x32x16_bf16 v[48:63], v[152:155], v[210:213], v[48:63]
	ds_read_b64_tr_b16 v[210:211], v173 offset:0x6200
	ds_read_b64_tr_b16 v[212:213], v173 offset:0x6a00
	v_mfma_f32_32x32x16_bf16 v[48:63], v[156:159], v[220:223], v[48:63]
	ds_read_b64_tr_b16 v[220:221], v173 offset:0x7200
	ds_read_b64_tr_b16 v[222:223], v173 offset:0x7a00
	s_waitcnt lgkmcnt(0)
	v_mfma_f32_32x32x16_bf16 v[32:47], v[144:147], v[194:197], v[32:47]
	ds_read_b64_tr_b16 v[194:195], v173 offset:0x4400
	ds_read_b64_tr_b16 v[196:197], v173 offset:0x4c00
	v_mfma_f32_32x32x16_bf16 v[32:47], v[148:151], v[206:209], v[32:47]
	ds_read_b64_tr_b16 v[206:207], v173 offset:0x5400
	ds_read_b64_tr_b16 v[208:209], v173 offset:0x5c00
	v_mfma_f32_32x32x16_bf16 v[32:47], v[152:155], v[210:213], v[32:47]
	ds_read_b64_tr_b16 v[210:211], v173 offset:0x6400
	ds_read_b64_tr_b16 v[212:213], v173 offset:0x6c00
	v_mfma_f32_32x32x16_bf16 v[32:47], v[156:159], v[220:223], v[32:47]
	ds_read_b64_tr_b16 v[220:221], v173 offset:0x7400
	ds_read_b64_tr_b16 v[222:223], v173 offset:0x7c00
	s_waitcnt lgkmcnt(0)
	v_mfma_f32_32x32x16_bf16 v[16:31], v[144:147], v[194:197], v[16:31]
	ds_read_b64_tr_b16 v[194:195], v173 offset:0x4600
	ds_read_b64_tr_b16 v[196:197], v173 offset:0x4e00
	v_mfma_f32_32x32x16_bf16 v[16:31], v[148:151], v[206:209], v[16:31]
	ds_read_b64_tr_b16 v[206:207], v173 offset:0x5600
	ds_read_b64_tr_b16 v[208:209], v173 offset:0x5e00
	v_mfma_f32_32x32x16_bf16 v[16:31], v[152:155], v[210:213], v[16:31]
	ds_read_b64_tr_b16 v[210:211], v173 offset:0x6600
	ds_read_b64_tr_b16 v[212:213], v173 offset:0x6e00
	v_mfma_f32_32x32x16_bf16 v[16:31], v[156:159], v[220:223], v[16:31]
	ds_read_b64_tr_b16 v[220:221], v173 offset:0x7600
	ds_read_b64_tr_b16 v[222:223], v173 offset:0x7e00
	s_waitcnt lgkmcnt(0)
	v_mfma_f32_32x32x16_bf16 v[0:15], v[144:147], v[194:197], v[0:15]
	s_cmp_le_i32 s0, s19
	s_cselect_b64 s[0:1], -1, 0
	s_cmp_gt_i32 s27, s24
	s_cselect_b64 s[28:29], -1, 0
	s_and_b64 s[0:1], s[0:1], s[28:29]
	s_and_b64 vcc, exec, s[0:1]
	v_mfma_f32_32x32x16_bf16 v[0:15], v[148:151], v[206:209], v[0:15]
	v_mfma_f32_32x32x16_bf16 v[0:15], v[152:155], v[210:213], v[0:15]
	v_mfma_f32_32x32x16_bf16 v[0:15], v[156:159], v[220:223], v[0:15]
	s_cmp_eq_u64 s[2:3], 0
	s_cbranch_scc1 .Lhs2_no_kstage
	s_waitcnt vmcnt(0)
	ds_write_b128 v176, v[136:139] offset:49152
	ds_write_b128 v176, v[140:143] offset:53248

.LBB0_211:
	ds_read_b128 v[64:67], v180 offset:49152
	ds_read_b128 v[68:71], v180 offset:53248
	s_waitcnt lgkmcnt(1)
	v_mfma_f32_32x32x16_bf16 v[80:95], v[64:67], v[124:127], 0
	s_waitcnt lgkmcnt(0)
	v_mfma_f32_32x32x16_bf16 v[64:79], v[68:71], v[124:127], 0
	ds_read_b128 v[124:127], v179 offset:49152
	ds_read_b128 v[128:131], v179 offset:53248
	s_waitcnt lgkmcnt(1)
	v_mfma_f32_32x32x16_bf16 v[80:95], v[124:127], v[120:123], v[80:95]
	s_waitcnt lgkmcnt(0)
	v_mfma_f32_32x32x16_bf16 v[64:79], v[128:131], v[120:123], v[64:79]
	ds_read_b128 v[120:123], v165 offset:49152
	ds_read_b128 v[124:127], v165 offset:53248
	s_waitcnt lgkmcnt(1)
	v_mfma_f32_32x32x16_bf16 v[80:95], v[120:123], v[116:119], v[80:95]
	s_waitcnt lgkmcnt(0)
	v_mfma_f32_32x32x16_bf16 v[64:79], v[124:127], v[116:119], v[64:79]
	ds_read_b128 v[116:119], v163 offset:49152
	ds_read_b128 v[120:123], v163 offset:53248
	s_waitcnt lgkmcnt(1)
	v_mfma_f32_32x32x16_bf16 v[80:95], v[116:119], v[112:115], v[80:95]
	s_waitcnt lgkmcnt(0)
	v_mfma_f32_32x32x16_bf16 v[64:79], v[120:123], v[112:115], v[64:79]
	ds_read_b128 v[112:115], v180 offset:57344
	ds_read_b128 v[116:119], v180 offset:61440
	s_waitcnt lgkmcnt(1)
	v_mfma_f32_32x32x16_bf16 v[80:95], v[112:115], v[108:111], v[80:95]
	s_waitcnt lgkmcnt(0)
	v_mfma_f32_32x32x16_bf16 v[64:79], v[116:119], v[108:111], v[64:79]
	ds_read_b128 v[108:111], v179 offset:57344
	ds_read_b128 v[112:115], v179 offset:61440
	s_waitcnt lgkmcnt(1)
	v_mfma_f32_32x32x16_bf16 v[80:95], v[108:111], v[104:107], v[80:95]
	s_waitcnt lgkmcnt(0)
	v_mfma_f32_32x32x16_bf16 v[64:79], v[112:115], v[104:107], v[64:79]
	ds_read_b128 v[104:107], v165 offset:57344
	ds_read_b128 v[108:111], v165 offset:61440
	s_waitcnt lgkmcnt(1)
	v_mfma_f32_32x32x16_bf16 v[80:95], v[104:107], v[100:103], v[80:95]
	s_waitcnt lgkmcnt(0)
	v_mfma_f32_32x32x16_bf16 v[64:79], v[108:111], v[100:103], v[64:79]
	ds_read_b128 v[100:103], v163 offset:57344
	ds_read_b128 v[104:107], v163 offset:61440
	s_waitcnt lgkmcnt(1)
	v_mfma_f32_32x32x16_bf16 v[80:95], v[100:103], v[96:99], v[80:95]
	s_waitcnt lgkmcnt(0)
	v_mfma_f32_32x32x16_bf16 v[64:79], v[104:107], v[96:99], v[64:79]
	v_lshlrev_b64 v[96:97], 8, v[160:161]
	v_ashrrev_i32_e32 v163, 31, v162
	v_lshl_add_u64 v[98:99], s[8:9], 0, v[96:97]
	v_lshlrev_b64 v[100:101], 8, v[162:163]
	v_lshl_add_u64 v[98:99], v[98:99], 0, v[184:185]
	v_lshl_add_u64 v[102:103], s[8:9], 0, v[100:101]
	v_lshl_add_u64 v[96:97], s[12:13], 0, v[96:97]
	v_lshl_add_u64 v[102:103], v[102:103], 0, v[184:185]
	global_load_dwordx4 v[128:131], v[98:99], off
	global_load_dwordx4 v[132:135], v[102:103], off
	v_lshl_add_u64 v[96:97], v[96:97], 0, v[184:185]
	v_lshl_add_u64 v[98:99], s[12:13], 0, v[100:101]
	v_lshl_add_u64 v[98:99], v[98:99], 0, v[184:185]
	global_load_dwordx4 v[136:139], v[96:97], off
	global_load_dwordx4 v[140:143], v[98:99], off
	v_or_b32_e32 v96, s18, v172
	v_ashrrev_i32_e32 v97, 31, v96
	v_lshlrev_b64 v[96:97], 8, v[96:97]
	v_lshl_add_u64 v[96:97], s[6:7], 0, v[96:97]
	v_mov_b32_e32 v165, v185
	v_lshl_add_u64 v[96:97], v[96:97], 0, v[164:165]
	global_load_dwordx4 v[124:127], v[96:97], off
	global_load_dwordx4 v[120:123], v[96:97], off offset:32
	global_load_dwordx4 v[116:119], v[96:97], off offset:64
	global_load_dwordx4 v[112:115], v[96:97], off offset:96
	global_load_dwordx4 v[108:111], v[96:97], off offset:128
	global_load_dwordx4 v[104:107], v[96:97], off offset:160
	global_load_dwordx4 v[100:103], v[96:97], off offset:192
	s_nop 0
	global_load_dwordx4 v[96:99], v[96:97], off offset:224
	v_exp_f32_e32 v165, v144
	v_add_f32_e32 v144, 0, v216
	v_add_f32_e32 v144, v219, v144
	v_add_f32_e32 v144, v213, v144
	v_add_f32_e32 v144, v217, v144
	v_add_f32_e32 v144, v212, v144
	v_add_f32_e32 v144, v214, v144
	v_add_f32_e32 v144, v210, v144
	v_add_f32_e32 v144, v211, v144
	v_add_f32_e32 v144, v207, v144
	v_add_f32_e32 v144, v209, v144
	v_add_f32_e32 v144, v206, v144
	v_add_f32_e32 v144, v208, v144
	v_exp_f32_e32 v156, v156
	v_add_f32_e32 v144, v195, v144
	v_exp_f32_e32 v157, v157
	v_add_f32_e32 v144, v197, v144
	v_exp_f32_e32 v160, v154
	v_add_f32_e32 v144, v194, v144
	v_exp_f32_e32 v155, v155
	v_add_f32_e32 v144, v196, v144
	v_exp_f32_e32 v161, v150
	v_add_f32_e32 v144, v156, v144
	v_exp_f32_e32 v162, v151
	v_add_f32_e32 v144, v157, v144
	v_exp_f32_e32 v163, v148
	v_add_f32_e32 v144, v160, v144
	v_exp_f32_e32 v164, v149
	v_add_f32_e32 v144, v155, v144
	v_add_f32_e32 v144, v161, v144
	v_exp_f32_e32 v166, v145
	v_add_f32_e32 v144, v162, v144
	v_exp_f32_e32 v167, v158
	v_add_f32_e32 v144, v163, v144
	v_exp_f32_e32 v159, v159
	v_add_f32_e32 v144, v164, v144
	v_exp_f32_e32 v168, v152
	v_add_f32_e32 v144, v165, v144
	v_exp_f32_e32 v169, v153
	v_add_f32_e32 v144, v166, v144
	v_exp_f32_e32 v179, v146
	v_add_f32_e32 v144, v167, v144
	v_exp_f32_e32 v180, v147
	v_add_f32_e32 v144, v159, v144
	v_add_f32_e32 v144, v168, v144
	v_add_f32_e32 v144, v169, v144
	v_add_f32_e32 v144, v179, v144
	v_add_f32_e32 v144, v180, v144
	v_mov_b32_e32 v145, v144
	s_nop 1
	v_permlane32_swap_b32_e32 v144, v145
	s_nop 0
	v_cvt_pk_bf16_f32 v146, v216, v219
	s_nop 0
	v_cvt_pk_bf16_f32 v147, v213, v217
	s_nop 0
	v_cvt_pk_bf16_f32 v148, v212, v214
	s_nop 0
	v_cvt_pk_bf16_f32 v149, v210, v211
	s_nop 0
	v_cvt_pk_bf16_f32 v150, v207, v209
	s_nop 0
	v_cvt_pk_bf16_f32 v151, v206, v208
	s_nop 0
	v_cvt_pk_bf16_f32 v152, v195, v197
	s_nop 0
	v_cvt_pk_bf16_f32 v153, v194, v196
	s_nop 0
	v_cvt_pk_bf16_f32 v154, v156, v157
	s_nop 0
	v_cvt_pk_bf16_f32 v155, v160, v155
	s_nop 0
	v_cvt_pk_bf16_f32 v156, v161, v162
	s_nop 0
	v_cvt_pk_bf16_f32 v157, v163, v164
	s_nop 0
	v_cvt_pk_bf16_f32 v158, v165, v166
	s_nop 0
	v_cvt_pk_bf16_f32 v159, v167, v159
	s_nop 0
	v_cvt_pk_bf16_f32 v160, v168, v169
	s_nop 0
	v_cvt_pk_bf16_f32 v161, v179, v180
	s_nop 0
	v_permlane32_swap_b32_e32 v146, v148
	v_permlane32_swap_b32_e32 v147, v149
	v_permlane32_swap_b32_e32 v150, v152
	v_permlane32_swap_b32_e32 v151, v153
	v_permlane32_swap_b32_e32 v154, v156
	v_permlane32_swap_b32_e32 v155, v157
	v_permlane32_swap_b32_e32 v158, v160
	v_permlane32_swap_b32_e32 v159, v161
	ds_read_b64_tr_b16 v[162:163], v173 offset:0
	ds_read_b64_tr_b16 v[164:165], v173 offset:0x800
	ds_read_b64_tr_b16 v[166:167], v173 offset:0x1000
	ds_read_b64_tr_b16 v[168:169], v173 offset:0x1800
	ds_read_b64_tr_b16 v[180:181], v173 offset:0x2000
	ds_read_b64_tr_b16 v[182:183], v173 offset:0x2800
	ds_read_b64_tr_b16 v[194:195], v173 offset:0x3000
	ds_read_b64_tr_b16 v[196:197], v173 offset:0x3800
	s_waitcnt lgkmcnt(0)
	s_nop 0
	v_mfma_f32_32x32x16_bf16 v[48:63], v[146:149], v[162:165], v[48:63]
	ds_read_b64_tr_b16 v[162:163], v173 offset:0x200
	ds_read_b64_tr_b16 v[164:165], v173 offset:0xa00
	v_mfma_f32_32x32x16_bf16 v[48:63], v[150:153], v[166:169], v[48:63]
	ds_read_b64_tr_b16 v[166:167], v173 offset:0x1200
	ds_read_b64_tr_b16 v[168:169], v173 offset:0x1a00
	v_mfma_f32_32x32x16_bf16 v[48:63], v[154:157], v[180:183], v[48:63]
	ds_read_b64_tr_b16 v[180:181], v173 offset:0x2200
	ds_read_b64_tr_b16 v[182:183], v173 offset:0x2a00
	v_mfma_f32_32x32x16_bf16 v[48:63], v[158:161], v[194:197], v[48:63]
	ds_read_b64_tr_b16 v[194:195], v173 offset:0x3200
	ds_read_b64_tr_b16 v[196:197], v173 offset:0x3a00
	s_waitcnt lgkmcnt(0)
	v_mfma_f32_32x32x16_bf16 v[32:47], v[146:149], v[162:165], v[32:47]
	ds_read_b64_tr_b16 v[162:163], v173 offset:0x400
	ds_read_b64_tr_b16 v[164:165], v173 offset:0xc00
	v_mfma_f32_32x32x16_bf16 v[32:47], v[150:153], v[166:169], v[32:47]
	ds_read_b64_tr_b16 v[166:167], v173 offset:0x1400
	ds_read_b64_tr_b16 v[168:169], v173 offset:0x1c00
	v_mfma_f32_32x32x16_bf16 v[32:47], v[154:157], v[180:183], v[32:47]
	ds_read_b64_tr_b16 v[180:181], v173 offset:0x2400
	ds_read_b64_tr_b16 v[182:183], v173 offset:0x2c00
	v_mfma_f32_32x32x16_bf16 v[32:47], v[158:161], v[194:197], v[32:47]
	ds_read_b64_tr_b16 v[194:195], v173 offset:0x3400
	ds_read_b64_tr_b16 v[196:197], v173 offset:0x3c00
	s_waitcnt lgkmcnt(0)
	v_mfma_f32_32x32x16_bf16 v[16:31], v[146:149], v[162:165], v[16:31]
	ds_read_b64_tr_b16 v[162:163], v173 offset:0x600
	ds_read_b64_tr_b16 v[164:165], v173 offset:0xe00
	v_mfma_f32_32x32x16_bf16 v[16:31], v[150:153], v[166:169], v[16:31]
	ds_read_b64_tr_b16 v[166:167], v173 offset:0x1600
	ds_read_b64_tr_b16 v[168:169], v173 offset:0x1e00
	v_mfma_f32_32x32x16_bf16 v[16:31], v[154:157], v[180:183], v[16:31]
	ds_read_b64_tr_b16 v[180:181], v173 offset:0x2600
	ds_read_b64_tr_b16 v[182:183], v173 offset:0x2e00
	v_mfma_f32_32x32x16_bf16 v[16:31], v[158:161], v[194:197], v[16:31]
	ds_read_b64_tr_b16 v[194:195], v173 offset:0x3600
	ds_read_b64_tr_b16 v[196:197], v173 offset:0x3e00
	s_waitcnt lgkmcnt(0)
	v_mfma_f32_32x32x16_bf16 v[0:15], v[146:149], v[162:165], v[0:15]
	s_lshl_b32 s1, s23, 6
	s_sub_i32 s0, s1, 64
	s_add_i32 s1, s1, -1
	s_cmp_le_i32 s1, s19
	s_cselect_b64 s[2:3], -1, 0
	s_cmp_gt_i32 s0, s24
	s_cselect_b64 s[24:25], -1, 0
	v_mfma_f32_32x32x16_bf16 v[0:15], v[150:153], v[166:169], v[0:15]
	s_and_b64 s[2:3], s[2:3], s[24:25]
	s_and_b64 vcc, exec, s[2:3]
	v_mfma_f32_32x32x16_bf16 v[0:15], v[154:157], v[180:183], v[0:15]
	v_mfma_f32_32x32x16_bf16 v[0:15], v[158:161], v[194:197], v[0:15]
	s_cbranch_vccnz .LBB0_213
	v_subrev_u32_e32 v146, s0, v178
	v_cmp_gt_u32_e32 vcc, s73, v146
	v_add_u32_e32 v147, 0xffffdfe0, v146
	s_nop 0
	v_cndmask_b32_e32 v80, v202, v80, vcc
	v_cmp_lt_u32_e32 vcc, s95, v147
	v_add_u32_e32 v147, 0xffffdfff, v146
	s_nop 0
	v_cndmask_b32_e32 v64, v202, v64, vcc
	v_cmp_lt_u32_e32 vcc, s95, v147
	v_add_u32_e32 v147, 0xffffdfdf, v146
	s_nop 0
	v_cndmask_b32_e32 v81, v202, v81, vcc
	v_cmp_lt_u32_e32 vcc, s95, v147
	v_add_u32_e32 v147, 0xffffdffe, v146
	s_nop 0
	v_cndmask_b32_e32 v65, v202, v65, vcc
	v_cmp_lt_u32_e32 vcc, s95, v147
	v_add_u32_e32 v147, 0xffffdfde, v146
	s_nop 0
	v_cndmask_b32_e32 v82, v202, v82, vcc
	v_cmp_lt_u32_e32 vcc, s95, v147
	v_add_u32_e32 v147, 0xffffdffd, v146
	s_nop 0
	v_cndmask_b32_e32 v66, v202, v66, vcc
	v_cmp_lt_u32_e32 vcc, s95, v147
	v_add_u32_e32 v147, 0xffffdfdd, v146
	s_nop 0
	v_cndmask_b32_e32 v83, v202, v83, vcc
	v_cmp_lt_u32_e32 vcc, s95, v147
	v_add_u32_e32 v147, 0xffffdff8, v146
	s_nop 0
	v_cndmask_b32_e32 v67, v202, v67, vcc
	v_cmp_lt_u32_e32 vcc, s95, v147
	v_add_u32_e32 v147, 0xffffdfd8, v146
	s_nop 0
	v_cndmask_b32_e32 v84, v202, v84, vcc
	v_cmp_lt_u32_e32 vcc, s95, v147
	v_add_u32_e32 v147, 0xffffdff7, v146
	s_nop 0
	v_cndmask_b32_e32 v68, v202, v68, vcc
	v_cmp_lt_u32_e32 vcc, s95, v147
	v_add_u32_e32 v147, 0xffffdfd7, v146
	s_nop 0
	v_cndmask_b32_e32 v85, v202, v85, vcc
	v_cmp_lt_u32_e32 vcc, s95, v147
	v_add_u32_e32 v147, 0xffffdff6, v146
	s_nop 0
	v_cndmask_b32_e32 v69, v202, v69, vcc
	v_cmp_lt_u32_e32 vcc, s95, v147
	v_add_u32_e32 v147, 0xffffdfd6, v146
	s_nop 0
	v_cndmask_b32_e32 v86, v202, v86, vcc
	v_cmp_lt_u32_e32 vcc, s95, v147
	v_add_u32_e32 v147, 0xffffdff5, v146
	s_nop 0
	v_cndmask_b32_e32 v70, v202, v70, vcc
	v_cmp_lt_u32_e32 vcc, s95, v147
	v_add_u32_e32 v147, 0xffffdfd5, v146
	s_nop 0
	v_cndmask_b32_e32 v87, v202, v87, vcc
	v_cmp_lt_u32_e32 vcc, s95, v147
	v_add_u32_e32 v147, 0xffffdff0, v146
	s_nop 0
	v_cndmask_b32_e32 v71, v202, v71, vcc
	v_cmp_lt_u32_e32 vcc, s95, v147
	v_add_u32_e32 v147, 0xffffdfd0, v146
	s_nop 0
	v_cndmask_b32_e32 v88, v202, v88, vcc
	v_cmp_lt_u32_e32 vcc, s95, v147
	v_add_u32_e32 v147, 0xffffdfef, v146
	s_nop 0
	v_cndmask_b32_e32 v72, v202, v72, vcc
	v_cmp_lt_u32_e32 vcc, s95, v147
	v_add_u32_e32 v147, 0xffffdfcf, v146
	s_nop 0
	v_cndmask_b32_e32 v89, v202, v89, vcc
	v_cmp_lt_u32_e32 vcc, s95, v147
	v_add_u32_e32 v147, 0xffffdfee, v146
	s_nop 0
	v_cndmask_b32_e32 v73, v202, v73, vcc
	v_cmp_lt_u32_e32 vcc, s95, v147
	v_add_u32_e32 v147, 0xffffdfce, v146
	s_nop 0
	v_cndmask_b32_e32 v90, v202, v90, vcc
	v_cmp_lt_u32_e32 vcc, s95, v147
	v_add_u32_e32 v147, 0xffffdfed, v146
	s_nop 0
	v_cndmask_b32_e32 v74, v202, v74, vcc
	v_cmp_lt_u32_e32 vcc, s95, v147
	v_add_u32_e32 v147, 0xffffdfcd, v146
	s_nop 0
	v_cndmask_b32_e32 v91, v202, v91, vcc
	v_cmp_lt_u32_e32 vcc, s95, v147
	v_add_u32_e32 v147, 0xffffdfe8, v146
	s_nop 0
	v_cndmask_b32_e32 v75, v202, v75, vcc
	v_cmp_lt_u32_e32 vcc, s95, v147
	v_add_u32_e32 v147, 0xffffdfc8, v146
	s_nop 0
	v_cndmask_b32_e32 v92, v202, v92, vcc
	v_cmp_lt_u32_e32 vcc, s95, v147
	v_add_u32_e32 v147, 0xffffdfe7, v146
	s_nop 0
	v_cndmask_b32_e32 v76, v202, v76, vcc
	v_cmp_lt_u32_e32 vcc, s95, v147
	v_add_u32_e32 v147, 0xffffdfc7, v146
	s_nop 0
	v_cndmask_b32_e32 v93, v202, v93, vcc
	v_cmp_lt_u32_e32 vcc, s95, v147
	v_add_u32_e32 v147, 0xffffdfe6, v146
	s_nop 0
	v_cndmask_b32_e32 v77, v202, v77, vcc
	v_cmp_lt_u32_e32 vcc, s95, v147
	v_add_u32_e32 v147, 0xffffdfc6, v146
	s_nop 0
	v_cndmask_b32_e32 v94, v202, v94, vcc
	v_cmp_lt_u32_e32 vcc, s95, v147
	v_add_u32_e32 v147, 0xffffdfe5, v146
	v_add_u32_e32 v146, 0xffffdfc5, v146
	v_cndmask_b32_e32 v78, v202, v78, vcc
	v_cmp_lt_u32_e32 vcc, s95, v147
	s_nop 1
	v_cndmask_b32_e32 v95, v202, v95, vcc
	v_cmp_lt_u32_e32 vcc, s95, v146
	s_nop 1
	v_cndmask_b32_e32 v79, v202, v79, vcc

.LBB0_217:
	v_cndmask_b32_e64 v147, v147, v186, s[0:1]
	v_mul_f32_e32 v147, 0xbe0293ee, v147
	v_fmamk_f32 v80, v80, 0x3e0293ee, v147
	v_fmamk_f32 v81, v81, 0x3e0293ee, v147
	v_fmamk_f32 v148, v82, 0x3e0293ee, v147
	v_exp_f32_e32 v82, v80
	v_fmamk_f32 v149, v84, 0x3e0293ee, v147
	v_exp_f32_e32 v84, v81
	v_fmamk_f32 v83, v83, 0x3e0293ee, v147
	v_exp_f32_e32 v80, v148
	v_fmamk_f32 v64, v64, 0x3e0293ee, v147
	v_exp_f32_e32 v83, v83
	v_fmamk_f32 v150, v85, 0x3e0293ee, v147
	v_fmamk_f32 v159, v94, 0x3e0293ee, v147
	v_fmamk_f32 v94, v75, 0x3e0293ee, v147
	v_exp_f32_e32 v75, v149
	v_exp_f32_e32 v148, v64
	v_add_f32_e32 v64, 0, v82
	v_fmamk_f32 v151, v86, 0x3e0293ee, v147
	v_exp_f32_e32 v81, v150
	v_add_f32_e32 v64, v84, v64
	v_fmamk_f32 v152, v87, 0x3e0293ee, v147
	v_fmamk_f32 v158, v93, 0x3e0293ee, v147
	v_fmamk_f32 v93, v74, 0x3e0293ee, v147
	v_exp_f32_e32 v74, v151
	v_add_f32_e32 v64, v80, v64
	v_fmamk_f32 v153, v88, 0x3e0293ee, v147
	v_fmamk_f32 v160, v95, 0x3e0293ee, v147
	v_fmamk_f32 v95, v76, 0x3e0293ee, v147
	v_exp_f32_e32 v76, v152
	v_add_f32_e32 v64, v83, v64
	v_fmamk_f32 v154, v89, 0x3e0293ee, v147
	v_fmamk_f32 v155, v90, 0x3e0293ee, v147
	v_fmamk_f32 v90, v71, 0x3e0293ee, v147
	v_exp_f32_e32 v71, v153
	v_add_f32_e32 v64, v75, v64
	v_fmamk_f32 v157, v92, 0x3e0293ee, v147
	v_fmamk_f32 v92, v73, 0x3e0293ee, v147
	v_exp_f32_e32 v73, v154
	v_add_f32_e32 v64, v81, v64
	v_fmamk_f32 v156, v91, 0x3e0293ee, v147
	v_fmamk_f32 v88, v69, 0x3e0293ee, v147
	v_exp_f32_e32 v69, v155
	v_add_f32_e32 v64, v74, v64
	v_fmamk_f32 v91, v72, 0x3e0293ee, v147
	v_exp_f32_e32 v72, v156
	v_add_f32_e32 v64, v76, v64
	v_fmamk_f32 v86, v67, 0x3e0293ee, v147
	v_exp_f32_e32 v67, v157
	v_add_f32_e32 v64, v71, v64
	v_fmamk_f32 v89, v70, 0x3e0293ee, v147
	v_exp_f32_e32 v70, v158
	v_add_f32_e32 v64, v73, v64
	v_fmamk_f32 v85, v66, 0x3e0293ee, v147
	v_exp_f32_e32 v66, v159
	v_add_f32_e32 v64, v69, v64
	v_fmamk_f32 v87, v68, 0x3e0293ee, v147
	v_exp_f32_e32 v68, v160
	v_add_f32_e32 v64, v72, v64
	v_fmamk_f32 v65, v65, 0x3e0293ee, v147
	v_add_f32_e32 v64, v67, v64
	v_exp_f32_e32 v149, v65
	v_add_f32_e32 v64, v70, v64
	v_exp_f32_e32 v85, v85
	v_add_f32_e32 v64, v66, v64
	v_exp_f32_e32 v86, v86
	v_add_f32_e32 v64, v68, v64
	v_exp_f32_e32 v87, v87
	v_add_f32_e32 v64, v148, v64
	v_exp_f32_e32 v88, v88
	v_add_f32_e32 v64, v149, v64
	v_exp_f32_e32 v89, v89
	v_add_f32_e32 v64, v85, v64
	v_exp_f32_e32 v90, v90
	v_add_f32_e32 v64, v86, v64
	v_exp_f32_e32 v91, v91
	v_add_f32_e32 v64, v87, v64
	v_exp_f32_e32 v92, v92
	v_add_f32_e32 v64, v88, v64
	v_exp_f32_e32 v93, v93
	v_add_f32_e32 v64, v89, v64
	v_exp_f32_e32 v94, v94
	v_add_f32_e32 v64, v90, v64
	v_fmamk_f32 v77, v77, 0x3e0293ee, v147
	v_exp_f32_e32 v95, v95
	v_add_f32_e32 v64, v91, v64
	v_fmamk_f32 v78, v78, 0x3e0293ee, v147
	v_exp_f32_e32 v150, v77
	v_add_f32_e32 v64, v92, v64
	v_fmac_f32_e32 v147, 0x3e0293ee, v79
	v_exp_f32_e32 v151, v78
	v_add_f32_e32 v64, v93, v64
	v_exp_f32_e32 v147, v147
	v_add_f32_e32 v64, v94, v64
	v_add_f32_e32 v64, v95, v64
	v_add_f32_e32 v64, v150, v64
	v_add_f32_e32 v64, v151, v64
	v_add_f32_e32 v64, v147, v64
	v_mov_b32_e32 v65, v64
	s_nop 1
	v_permlane32_swap_b32_e32 v64, v65
	s_nop 0
	v_cvt_pk_bf16_f32 v78, v82, v84
	s_nop 0
	v_cvt_pk_bf16_f32 v79, v80, v83
	s_nop 0
	v_cvt_pk_bf16_f32 v80, v75, v81
	s_nop 0
	v_cvt_pk_bf16_f32 v81, v74, v76
	s_nop 0
	v_cvt_pk_bf16_f32 v74, v71, v73
	s_nop 0
	v_cvt_pk_bf16_f32 v75, v69, v72
	s_nop 0
	v_cvt_pk_bf16_f32 v76, v67, v70
	s_nop 0
	v_cvt_pk_bf16_f32 v77, v66, v68
	s_nop 0
	v_cvt_pk_bf16_f32 v66, v148, v149
	s_nop 0
	v_cvt_pk_bf16_f32 v67, v85, v86
	s_nop 0
	v_cvt_pk_bf16_f32 v68, v87, v88
	s_nop 0
	v_cvt_pk_bf16_f32 v69, v89, v90
	s_nop 0
	v_cvt_pk_bf16_f32 v70, v91, v92
	s_nop 0
	v_cvt_pk_bf16_f32 v71, v93, v94
	s_nop 0
	v_cvt_pk_bf16_f32 v72, v95, v150
	s_nop 0
	v_cvt_pk_bf16_f32 v73, v151, v147
	s_nop 0
	v_permlane32_swap_b32_e32 v78, v80
	v_permlane32_swap_b32_e32 v79, v81
	v_permlane32_swap_b32_e32 v74, v76
	v_permlane32_swap_b32_e32 v75, v77
	v_permlane32_swap_b32_e32 v66, v68
	v_permlane32_swap_b32_e32 v67, v69
	v_permlane32_swap_b32_e32 v70, v72
	v_permlane32_swap_b32_e32 v71, v73
	ds_read_b64_tr_b16 v[82:83], v173 offset:0x4000
	ds_read_b64_tr_b16 v[84:85], v173 offset:0x4800
	ds_read_b64_tr_b16 v[86:87], v173 offset:0x5000
	ds_read_b64_tr_b16 v[88:89], v173 offset:0x5800
	ds_read_b64_tr_b16 v[90:91], v173 offset:0x6000
	ds_read_b64_tr_b16 v[92:93], v173 offset:0x6800
	ds_read_b64_tr_b16 v[148:149], v173 offset:0x7000
	ds_read_b64_tr_b16 v[150:151], v173 offset:0x7800
	s_waitcnt lgkmcnt(0)
	s_nop 0
	v_mfma_f32_32x32x16_bf16 v[48:63], v[78:81], v[82:85], v[48:63]
	ds_read_b64_tr_b16 v[82:83], v173 offset:0x4200
	ds_read_b64_tr_b16 v[84:85], v173 offset:0x4a00
	v_mfma_f32_32x32x16_bf16 v[48:63], v[74:77], v[86:89], v[48:63]
	ds_read_b64_tr_b16 v[86:87], v173 offset:0x5200
	ds_read_b64_tr_b16 v[88:89], v173 offset:0x5a00
	v_mfma_f32_32x32x16_bf16 v[48:63], v[66:69], v[90:93], v[48:63]
	ds_read_b64_tr_b16 v[90:91], v173 offset:0x6200
	ds_read_b64_tr_b16 v[92:93], v173 offset:0x6a00
	v_mfma_f32_32x32x16_bf16 v[48:63], v[70:73], v[148:151], v[48:63]
	ds_read_b64_tr_b16 v[148:149], v173 offset:0x7200
	ds_read_b64_tr_b16 v[150:151], v173 offset:0x7a00
	s_waitcnt lgkmcnt(0)
	v_mfma_f32_32x32x16_bf16 v[32:47], v[78:81], v[82:85], v[32:47]
	ds_read_b64_tr_b16 v[82:83], v173 offset:0x4400
	ds_read_b64_tr_b16 v[84:85], v173 offset:0x4c00
	v_mfma_f32_32x32x16_bf16 v[32:47], v[74:77], v[86:89], v[32:47]
	ds_read_b64_tr_b16 v[86:87], v173 offset:0x5400
	ds_read_b64_tr_b16 v[88:89], v173 offset:0x5c00
	v_mfma_f32_32x32x16_bf16 v[32:47], v[66:69], v[90:93], v[32:47]
	ds_read_b64_tr_b16 v[90:91], v173 offset:0x6400
	ds_read_b64_tr_b16 v[92:93], v173 offset:0x6c00
	v_mfma_f32_32x32x16_bf16 v[32:47], v[70:73], v[148:151], v[32:47]
	ds_read_b64_tr_b16 v[148:149], v173 offset:0x7400
	ds_read_b64_tr_b16 v[150:151], v173 offset:0x7c00
	s_waitcnt lgkmcnt(0)
	v_mfma_f32_32x32x16_bf16 v[16:31], v[78:81], v[82:85], v[16:31]
	ds_read_b64_tr_b16 v[82:83], v173 offset:0x4600
	ds_read_b64_tr_b16 v[84:85], v173 offset:0x4e00
	v_mfma_f32_32x32x16_bf16 v[16:31], v[74:77], v[86:89], v[16:31]
	ds_read_b64_tr_b16 v[86:87], v173 offset:0x5600
	ds_read_b64_tr_b16 v[88:89], v173 offset:0x5e00
	v_mfma_f32_32x32x16_bf16 v[16:31], v[66:69], v[90:93], v[16:31]
	ds_read_b64_tr_b16 v[90:91], v173 offset:0x6600
	ds_read_b64_tr_b16 v[92:93], v173 offset:0x6e00
	v_mfma_f32_32x32x16_bf16 v[16:31], v[70:73], v[148:151], v[16:31]
	ds_read_b64_tr_b16 v[148:149], v173 offset:0x7600
	ds_read_b64_tr_b16 v[150:151], v173 offset:0x7e00
	s_waitcnt lgkmcnt(0)
	v_mfma_f32_32x32x16_bf16 v[0:15], v[78:81], v[82:85], v[0:15]
	v_mfma_f32_32x32x16_bf16 v[0:15], v[74:77], v[86:89], v[0:15]
	v_mfma_f32_32x32x16_bf16 v[0:15], v[66:69], v[90:93], v[0:15]
	v_mfma_f32_32x32x16_bf16 v[0:15], v[70:73], v[148:151], v[0:15]
	s_waitcnt vmcnt(8)
	s_waitcnt vmcnt(9)
	ds_write_b128 v176, v[136:139] offset:32768
	s_waitcnt vmcnt(8)
	ds_write_b128 v176, v[140:143] offset:36864
	s_and_saveexec_b64 s[0:1], s[4:5]
	v_add_f32_e32 v66, v144, v145
	v_fmac_f32_e32 v66, v177, v192
	v_add_f32_e32 v64, v64, v65
	v_fmac_f32_e32 v64, v66, v146
	ds_write_b32 v175, v64
	s_or_b64 exec, exec, s[0:1]
	s_waitcnt lgkmcnt(0)
	ds_read_b128 v[76:79], v174
	ds_read_b128 v[72:75], v174 offset:32
	v_and_b32_e32 v80, 64, v204
	v_add_u32_e32 v80, 64, v80
	s_ashr_i32 s19, s18, 31
	s_waitcnt lgkmcnt(1)
	v_rcp_f32_e32 v82, v76
	v_xor_b32_e32 v76, 1, v204
	v_cmp_lt_i32_e32 vcc, v76, v80
	ds_read_b128 v[68:71], v174 offset:64
	ds_read_b128 v[64:67], v174 offset:96
	v_cndmask_b32_e32 v76, v204, v76, vcc
	v_lshlrev_b32_e32 v76, 2, v76
	v_mul_f32_e32 v48, v48, v82
	s_lshl_b64 s[0:1], s[18:19], 8
	s_nop 1
	v_mov_b32_dpp v83, v48 quad_perm:[1,0,3,2] row_mask:0xf bank_mask:0xf
	s_add_u32 s0, s16, s0
	s_addc_u32 s1, s17, s1
	v_and_b32_e32 v80, 1, v171
	v_lshlrev_b32_e32 v184, 1, v172
	v_cmp_eq_u32_e64 s[4:5], 0, v80
	v_lshl_add_u64 v[80:81], s[0:1], 0, v[184:185]
	v_lshlrev_b32_e32 v184, 10, v170
	v_lshl_add_u64 v[80:81], v[80:81], 0, v[184:185]
	s_and_saveexec_b64 s[0:1], s[4:5]
	s_cbranch_execz .LBB0_221
	s_waitcnt lgkmcnt(0)
	s_nop 0
	v_cvt_pk_bf16_f32 v48, v48, v83
	global_store_dword v[80:81], v48, off

.LBB0_720:
	s_or_b64 exec, exec, s[0:1]
	v_readlane_b32 s0, v246, 27
	v_readlane_b32 s1, v246, 28
	s_xor_b64 s[0:1], s[0:1], -1
	v_writelane_b32 v246, s0, 36
	v_mov_b32_e32 v46, v187
	s_nop 0
	v_writelane_b32 v246, s1, 37
	s_barrier
	v_readlane_b32 s0, v246, 31
	v_readlane_b32 s1, v246, 32
	v_readlane_b32 s1, v247, 60
	v_ashrrev_i32_e32 v0, 6, v46
	s_lshl_b32 s0, s0, 12
	v_add_u32_e32 v64, s1, v0
	v_cmp_gt_i32_e32 vcc, s82, v64
	s_and_saveexec_b64 s[2:3], vcc
	s_cbranch_execz .LBB0_723
	v_readlane_b32 s12, v247, 15
	s_ashr_i32 s1, s0, 31
	v_readlane_b32 s13, v247, 16
	v_readlane_b32 s16, v247, 19
	v_readlane_b32 s17, v247, 20
	s_lshl_b64 s[6:7], s[0:1], 2
	s_mov_b64 s[12:13], s[16:17]
	v_lshlrev_b32_e32 v0, 3, v46
	v_readlane_b32 s14, v247, 17
	v_readlane_b32 s15, v247, 18
	s_add_u32 s4, s12, s6
	v_ashrrev_i32_e32 v65, 31, v64
	v_and_b32_e32 v2, 0x1f8, v0
	s_mov_b64 s[10:11], s[14:15]
	s_addc_u32 s5, s13, s7
	v_lshlrev_b64 v[48:49], 12, v[64:65]
	s_add_u32 s6, s10, s6
	v_lshl_add_u64 v[0:1], s[36:37], 0, v[48:49]
	v_lshlrev_b32_e32 v184, 1, v2
	s_addc_u32 s7, s11, s7
	v_lshl_add_u64 v[0:1], v[0:1], 0, v[184:185]
	v_lshl_add_u64 v[32:33], s[36:37], 0, v[184:185]
	v_lshlrev_b32_e32 v184, 2, v2
	global_load_dwordx4 v[16:19], v[0:1], off offset:3072
	global_load_dwordx4 v[24:27], v[0:1], off offset:2048
	global_load_dwordx4 v[28:31], v[0:1], off offset:1024
	global_load_dwordx4 v[20:23], v[0:1], off
	s_nop 0
	global_load_dwordx4 v[0:3], v184, s[6:7]
	global_load_dwordx4 v[4:7], v184, s[6:7] offset:16
	global_load_dwordx4 v[8:11], v184, s[4:5]
	global_load_dwordx4 v[12:15], v184, s[4:5] offset:16
	v_and_b32_e32 v34, 64, v204
	v_add_u32_e32 v34, 64, v34
	v_xor_b32_e32 v35, 32, v204
	v_cmp_lt_i32_e32 vcc, v35, v34
	v_and_b32_e32 v46, 63, v46
	v_readlane_b32 s26, v247, 29
	v_cndmask_b32_e32 v35, v204, v35, vcc
	v_lshlrev_b32_e32 v65, 2, v35
	v_xor_b32_e32 v35, 16, v204
	v_cmp_lt_i32_e32 vcc, v35, v34
	v_readlane_b32 s27, v247, 30
	v_lshl_add_u64 v[36:37], s[4:5], 0, v[184:185]
	v_cndmask_b32_e32 v35, v204, v35, vcc
	v_lshlrev_b32_e32 v74, 2, v35
	v_xor_b32_e32 v35, 8, v204
	v_cmp_lt_i32_e32 vcc, v35, v34
	v_or_b32_e32 v40, 0x1000, v184
	v_mov_b32_e32 v41, v185
	v_cndmask_b32_e32 v35, v204, v35, vcc
	v_lshlrev_b32_e32 v75, 2, v35
	v_xor_b32_e32 v35, 4, v204
	v_cmp_lt_i32_e32 vcc, v35, v34
	v_lshl_or_b32 v48, v46, 4, v48
	s_mov_b64 s[26:27], 0xc040180
	v_cndmask_b32_e32 v35, v204, v35, vcc
	v_lshlrev_b32_e32 v76, 2, v35
	v_xor_b32_e32 v35, 2, v204
	v_cmp_lt_i32_e32 vcc, v35, v34
	v_lshl_add_u64 v[38:39], s[6:7], 0, v[40:41]
	v_lshl_add_u64 v[40:41], s[4:5], 0, v[40:41]
	v_cndmask_b32_e32 v35, v204, v35, vcc
	v_lshlrev_b32_e32 v77, 2, v35
	v_xor_b32_e32 v35, 1, v204
	v_cmp_lt_i32_e32 vcc, v35, v34
	v_lshl_add_u64 v[46:47], s[34:35], 0, v[48:49]
	v_readlane_b32 s18, v247, 21
	v_cndmask_b32_e32 v34, v204, v35, vcc
	v_lshlrev_b32_e32 v78, 2, v34
	v_lshl_add_u64 v[34:35], s[6:7], 0, v[184:185]
	v_or_b32_e32 v184, 0x1800, v184
	v_lshl_add_u64 v[42:43], s[6:7], 0, v[184:185]
	v_lshl_add_u64 v[44:45], s[4:5], 0, v[184:185]
	s_mov_b64 s[4:5], 0
	v_readlane_b32 s19, v247, 22
	v_readlane_b32 s20, v247, 23
	v_readlane_b32 s21, v247, 24
	v_readlane_b32 s22, v247, 25
	v_readlane_b32 s23, v247, 26
	v_readlane_b32 s24, v247, 27
	v_readlane_b32 s25, v247, 28
	global_load_dwordx4 v[128:131], v[36:37], off offset:2048
	global_load_dwordx4 v[132:135], v[34:35], off offset:2048
	global_load_dwordx4 v[136:139], v[34:35], off offset:2064
	global_load_dwordx4 v[140:143], v[36:37], off offset:2064
	global_load_dwordx4 v[144:147], v[40:41], off
	global_load_dwordx4 v[148:151], v[38:39], off
	global_load_dwordx4 v[152:155], v[38:39], off offset:16
	global_load_dwordx4 v[156:159], v[40:41], off offset:16
	global_load_dwordx4 v[160:163], v[44:45], off
	global_load_dwordx4 v[164:167], v[42:43], off
	global_load_dwordx4 v[168:171], v[42:43], off offset:16
	global_load_dwordx4 v[172:175], v[44:45], off offset:16
.LBB0_722:
	s_waitcnt vmcnt(4)
	v_lshlrev_b32_e32 v69, 16, v20
	v_lshlrev_b32_e32 v68, 16, v22
	v_and_b32_e32 v67, 0xffff0000, v20
	v_and_b32_e32 v66, 0xffff0000, v22
	v_lshlrev_b32_e32 v73, 16, v21
	v_lshlrev_b32_e32 v72, 16, v23
	v_and_b32_e32 v71, 0xffff0000, v21
	v_and_b32_e32 v70, 0xffff0000, v23
	v_lshlrev_b32_e32 v63, 16, v29
	v_lshlrev_b32_e32 v62, 16, v28
	v_and_b32_e32 v61, 0xffff0000, v29
	v_and_b32_e32 v60, 0xffff0000, v28
	v_and_b32_e32 v80, 0xffff0000, v19
	v_lshlrev_b32_e32 v81, 16, v19
	v_and_b32_e32 v82, 0xffff0000, v18
	v_lshlrev_b32_e32 v83, 16, v18
	v_pk_add_f32 v[18:19], v[68:69], v[66:67]
	v_pk_add_f32 v[20:21], v[72:73], v[70:71]
	v_pk_add_f32 v[22:23], v[62:63], v[60:61]
	v_pk_add_f32 v[18:19], v[20:21], v[18:19]
	v_lshlrev_b32_e32 v92, 16, v30
	v_and_b32_e32 v93, 0xffff0000, v30
	v_lshlrev_b32_e32 v94, 16, v31
	v_and_b32_e32 v95, 0xffff0000, v31
	v_pk_add_f32 v[20:21], v[22:23], v[22:23] op_sel_hi:[1,0]
	v_add_f32_e32 v19, 0, v19
	v_lshlrev_b32_e32 v54, 16, v24
	v_and_b32_e32 v52, 0xffff0000, v24
	v_lshlrev_b32_e32 v50, 16, v25
	v_and_b32_e32 v48, 0xffff0000, v25
	v_add_f32_e32 v53, v92, v93
	v_add_f32_e32 v55, v94, v95
	v_mov_b32_e32 v51, v21
	v_add_f32_e32 v49, v18, v19
	v_lshlrev_b32_e32 v59, 16, v27
	v_lshlrev_b32_e32 v58, 16, v26
	v_and_b32_e32 v57, 0xffff0000, v27
	v_and_b32_e32 v56, 0xffff0000, v26
	v_pk_add_f32 v[84:85], v[54:55], v[52:53]
	v_pk_add_f32 v[90:91], v[50:51], v[48:49]
	v_pk_add_f32 v[24:25], v[58:59], v[56:57]
	v_pk_add_f32 v[84:85], v[84:85], v[90:91]
	v_lshlrev_b32_e32 v96, 16, v16
	v_and_b32_e32 v97, 0xffff0000, v16
	v_lshlrev_b32_e32 v98, 16, v17
	v_and_b32_e32 v99, 0xffff0000, v17
	v_pk_add_f32 v[86:87], v[24:25], v[24:25] op_sel:[0,1] op_sel_hi:[1,0]
	v_pk_add_f32 v[84:85], v[84:85], v[84:85] op_sel:[0,1] op_sel_hi:[1,0]
	v_add_f32_e32 v26, v96, v97
	v_add_f32_e32 v28, v98, v99
	v_mov_b32_e32 v27, v81
	v_mov_b32_e32 v29, v80
	v_mov_b32_e32 v87, v83
	v_mov_b32_e32 v85, v82
	v_pk_add_f32 v[88:89], v[26:27], v[28:29]
	v_pk_add_f32 v[84:85], v[86:87], v[84:85]
	v_add_u32_e32 v79, s66, v64
	v_pk_add_f32 v[84:85], v[84:85], v[88:89]
	v_cmp_gt_i32_e32 vcc, s82, v79
	v_add_f32_e32 v49, v84, v85
	ds_bpermute_b32 v51, v65, v49
	v_cndmask_b32_e32 v16, v64, v79, vcc
	v_ashrrev_i32_e32 v17, 31, v16
	v_lshlrev_b64 v[16:17], 12, v[16:17]
	v_lshl_add_u64 v[16:17], v[32:33], 0, v[16:17]
	s_waitcnt lgkmcnt(0)
	v_add_f32_e32 v49, v49, v51
	ds_bpermute_b32 v51, v74, v49
	global_load_dwordx4 v[20:23], v[16:17], off
	global_load_dwordx4 v[28:31], v[16:17], off offset:1024
	global_load_dwordx4 v[24:27], v[16:17], off offset:2048
	s_nop 0
	global_load_dwordx4 v[16:19], v[16:17], off offset:3072
	s_waitcnt lgkmcnt(0)
	v_add_f32_e32 v49, v49, v51
	ds_bpermute_b32 v51, v75, v49
	s_waitcnt lgkmcnt(0)
	v_add_f32_e32 v49, v49, v51
	ds_bpermute_b32 v51, v76, v49
	s_waitcnt lgkmcnt(0)
	v_add_f32_e32 v49, v49, v51
	ds_bpermute_b32 v51, v77, v49
	s_waitcnt lgkmcnt(0)
	v_add_f32_e32 v49, v49, v51
	ds_bpermute_b32 v51, v78, v49
	s_waitcnt lgkmcnt(0)
	v_add_f32_e32 v49, v49, v51
	v_fmac_f32_e32 v67, 0xba000000, v49
	v_mul_f32_e32 v64, 0x3a000000, v49
	v_fmac_f32_e32 v69, 0xba000000, v49
	v_fmac_f32_e32 v73, 0xba000000, v49
	v_fmac_f32_e32 v71, 0xba000000, v49
	v_fmac_f32_e32 v68, 0xba000000, v49
	v_fmac_f32_e32 v66, 0xba000000, v49
	v_fmac_f32_e32 v72, 0xba000000, v49
	v_fmac_f32_e32 v70, 0xba000000, v49
	v_fmac_f32_e32 v62, 0xba000000, v49
	v_fmac_f32_e32 v60, 0xba000000, v49
	v_fmac_f32_e32 v63, 0xba000000, v49
	v_fmac_f32_e32 v61, 0xba000000, v49
	v_fmac_f32_e32 v92, 0xba000000, v49
	v_fmac_f32_e32 v93, 0xba000000, v49
	v_fmac_f32_e32 v94, 0xba000000, v49
	v_fmac_f32_e32 v95, 0xba000000, v49
	v_fmac_f32_e32 v54, 0xba000000, v49
	v_fmac_f32_e32 v52, 0xba000000, v49
	v_fmac_f32_e32 v50, 0xba000000, v49
	v_fmac_f32_e32 v48, 0xba000000, v49
	v_fmac_f32_e32 v58, 0xba000000, v49
	v_fmac_f32_e32 v56, 0xba000000, v49
	v_fmac_f32_e32 v59, 0xba000000, v49
	v_fmac_f32_e32 v57, 0xba000000, v49
	v_fmac_f32_e32 v96, 0xba000000, v49
	v_fmac_f32_e32 v97, 0xba000000, v49
	v_fmac_f32_e32 v98, 0xba000000, v49
	v_fmac_f32_e32 v99, 0xba000000, v49
	v_mul_f32_e32 v49, v67, v67
	v_fmac_f32_e32 v49, v69, v69
	v_fmac_f32_e32 v49, v73, v73
	v_fmac_f32_e32 v49, v71, v71
	v_fmac_f32_e32 v49, v68, v68
	v_fmac_f32_e32 v49, v66, v66
	v_fmac_f32_e32 v49, v72, v72
	v_fmac_f32_e32 v49, v70, v70
	v_fmac_f32_e32 v49, v62, v62
	v_fmac_f32_e32 v49, v60, v60
	v_fmac_f32_e32 v49, v63, v63
	v_fmac_f32_e32 v49, v61, v61
	v_fmac_f32_e32 v49, v92, v92
	v_fmac_f32_e32 v49, v93, v93
	v_fmac_f32_e32 v49, v94, v94
	v_fmac_f32_e32 v49, v95, v95
	v_fmac_f32_e32 v49, v54, v54
	v_fmac_f32_e32 v49, v52, v52
	v_fmac_f32_e32 v49, v50, v50
	v_fmac_f32_e32 v49, v48, v48
	v_fmac_f32_e32 v49, v58, v58
	v_fmac_f32_e32 v49, v56, v56
	v_fmac_f32_e32 v49, v59, v59
	v_fmac_f32_e32 v49, v57, v57
	v_fmac_f32_e32 v49, v96, v96
	v_fmac_f32_e32 v49, v97, v97
	v_pk_add_f32 v[88:89], v[82:83], v[64:65] op_sel_hi:[1,0] neg_lo:[0,1] neg_hi:[0,1]
	v_fmac_f32_e32 v49, v98, v98
	v_pk_add_f32 v[90:91], v[80:81], v[64:65] op_sel_hi:[1,0] neg_lo:[0,1] neg_hi:[0,1]
	v_pk_mul_f32 v[80:81], v[88:89], v[88:89]
	v_fmac_f32_e32 v49, v99, v99
	v_add_f32_e32 v49, v81, v49
	v_pk_mul_f32 v[82:83], v[90:91], v[90:91]
	v_add_f32_e32 v49, v80, v49
	v_add_f32_e32 v49, v83, v49
	v_add_f32_e32 v49, v82, v49
	ds_bpermute_b32 v51, v65, v49
	s_waitcnt lgkmcnt(0)
	v_add_f32_e32 v49, v49, v51
	ds_bpermute_b32 v51, v74, v49
	s_waitcnt lgkmcnt(0)
	v_add_f32_e32 v49, v49, v51
	ds_bpermute_b32 v51, v75, v49
	s_waitcnt lgkmcnt(0)
	v_add_f32_e32 v49, v49, v51
	ds_bpermute_b32 v51, v76, v49
	s_waitcnt lgkmcnt(0)
	v_add_f32_e32 v49, v49, v51
	ds_bpermute_b32 v51, v77, v49
	s_waitcnt lgkmcnt(0)
	v_add_f32_e32 v49, v49, v51
	ds_bpermute_b32 v51, v78, v49
	s_waitcnt lgkmcnt(0)
	v_add_f32_e32 v49, v49, v51
	v_fmamk_f32 v49, v49, 0x3a000000, v198
	v_mul_f32_e32 v51, 0x4b800000, v49
	v_cmp_gt_f32_e32 vcc, s40, v49
	s_nop 1
	v_cndmask_b32_e32 v49, v49, v51, vcc
	v_rsq_f32_e32 v49, v49
	s_nop 0
	v_mul_f32_e32 v51, 0x45800000, v49
	v_cndmask_b32_e32 v100, v49, v51, vcc
	v_mul_f32_e32 v66, v66, v100
	v_mul_f32_e32 v49, v69, v100
	v_mul_f32_e32 v51, v67, v100
	v_mul_f32_e32 v53, v73, v100
	v_mul_f32_e32 v55, v71, v100
	v_mul_f32_e32 v64, v68, v100
	v_mul_f32_e32 v67, v72, v100
	v_mul_f32_e32 v68, v70, v100
	s_waitcnt vmcnt(4)
	v_fma_f32 v69, v5, v66, v13
	v_fma_f32 v49, v0, v49, v8
	v_fma_f32 v51, v1, v51, v9
	v_fma_f32 v53, v2, v53, v10
	v_fma_f32 v55, v3, v55, v11
	v_fma_f32 v64, v4, v64, v12
	v_fma_f32 v70, v6, v67, v14
	v_fma_f32 v71, v7, v68, v15
	s_nop 0
	v_cvt_pk_bf16_f32 v66, v49, v51
	s_nop 0
	v_cvt_pk_bf16_f32 v67, v53, v55
	s_nop 0
	v_cvt_pk_bf16_f32 v68, v64, v69
	s_nop 0
	v_cvt_pk_bf16_f32 v69, v70, v71
	global_store_dwordx4 v[46:47], v[66:69], off
	v_mul_f32_e32 v49, v62, v100
	v_mul_f32_e32 v51, v60, v100
	v_mul_f32_e32 v53, v63, v100
	v_mul_f32_e32 v55, v61, v100
	v_mul_f32_e32 v60, v92, v100
	v_mul_f32_e32 v61, v93, v100
	v_mul_f32_e32 v62, v94, v100
	v_mul_f32_e32 v63, v95, v100
	v_mul_f32_e32 v50, v50, v100
	v_mul_f32_e32 v48, v48, v100
	v_cmp_lt_i32_e32 vcc, s41, v79
	s_or_b64 s[4:5], vcc, s[4:5]
	v_fma_f32 v49, v132, v49, v128
	v_fma_f32 v51, v133, v51, v129
	v_fma_f32 v53, v134, v53, v130
	v_fma_f32 v69, v135, v55, v131
	v_fma_f32 v55, v136, v60, v140
	v_fma_f32 v64, v137, v61, v141
	v_fma_f32 v66, v138, v62, v142
	v_fma_f32 v87, v139, v63, v143
	s_nop 0
	v_cvt_pk_bf16_f32 v60, v49, v51
	s_nop 0
	v_cvt_pk_bf16_f32 v61, v53, v69
	s_nop 0
	v_cvt_pk_bf16_f32 v62, v55, v64
	s_nop 0
	v_cvt_pk_bf16_f32 v63, v66, v87
	global_store_dwordx4 v[46:47], v[60:63], off offset:1024
	v_mul_f32_e32 v49, v54, v100
	v_mul_f32_e32 v51, v52, v100
	v_mul_f32_e32 v52, v58, v100
	v_mul_f32_e32 v53, v56, v100
	v_mul_f32_e32 v54, v59, v100
	v_mul_f32_e32 v55, v57, v100
	v_mov_b32_e32 v64, v79
	v_fma_f32 v49, v148, v49, v144
	v_fma_f32 v51, v149, v51, v145
	v_fma_f32 v50, v150, v50, v146
	v_fma_f32 v63, v151, v48, v147
	v_fma_f32 v52, v152, v52, v156
	v_fma_f32 v53, v153, v53, v157
	v_fma_f32 v54, v154, v54, v158
	v_fma_f32 v83, v155, v55, v159
	s_nop 0
	v_cvt_pk_bf16_f32 v48, v49, v51
	s_nop 0
	v_cvt_pk_bf16_f32 v49, v50, v63
	s_nop 0
	v_cvt_pk_bf16_f32 v50, v52, v53
	s_nop 0
	v_cvt_pk_bf16_f32 v51, v54, v83
	global_store_dwordx4 v[46:47], v[48:51], off offset:2048
	v_mul_f32_e32 v66, v96, v100
	v_mul_f32_e32 v67, v97, v100
	v_mul_f32_e32 v68, v98, v100
	v_mul_f32_e32 v69, v99, v100
	v_mul_f32_e32 v70, v89, v100
	v_mul_f32_e32 v71, v88, v100
	v_mul_f32_e32 v72, v91, v100
	v_mul_f32_e32 v73, v90, v100
	v_fma_f32 v48, v164, v66, v160
	v_fma_f32 v49, v165, v67, v161
	v_fma_f32 v50, v166, v68, v162
	v_fma_f32 v51, v167, v69, v163
	v_fma_f32 v52, v168, v70, v172
	v_fma_f32 v53, v169, v71, v173
	v_fma_f32 v54, v170, v72, v174
	v_fma_f32 v63, v171, v73, v175
	s_nop 0
	v_cvt_pk_bf16_f32 v48, v48, v49
	s_nop 0
	v_cvt_pk_bf16_f32 v49, v50, v51
	s_nop 0
	v_cvt_pk_bf16_f32 v50, v52, v53
	s_nop 0
	v_cvt_pk_bf16_f32 v51, v54, v63
	global_store_dwordx4 v[46:47], v[48:51], off offset:3072
	v_lshl_add_u64 v[46:47], v[46:47], 0, s[68:69]
	s_andn2_b64 exec, exec, s[4:5]
	s_cbranch_execnz .LBB0_722
